# GEMM tile heads (30 instances): 128 v_mov accumulator zeroing replaced by MFMA zeroing (0*0+0: 4 v_mov + 3 16x16x32 + 7 32x32x16 bf16 MFMAs)
# baseline (speedup 1.0000x reference)
;     __device__ __forceinline__ const char* pa(const Unit& u) const { return (const char*)(A + (size_t)u.pm * a_tile_stride + (size_t)((u.pn >> a_group_shift) * a_group_cols)); }
;     __device__ __forceinline__ const char* pb(const Unit& u) const { return (const char*)(Bt + (size_t)u.pn * b_tile_stride); }
;     __device__ __forceinline__ const char* pa(const Unit& u) const { return (const char*)(A + (size_t)u.pm * a_tile_stride + (size_t)u.pn * 512); }
; template <class PT, class Epi>
; __device__ __forceinline__ void gemm_phase_once(LAS unsigned char* lds, const PT& S, const Epi& E, bool epi_on) {
;     ...
;         const bool has_next = S.next(ui + 1, nxt);
;         const char* nA = has_next ? S.pa(nxt) : cA; const char* nB = has_next ? S.pb(nxt) : cB;
;         for (int t = 0; t < nt; t += 2) {
;             const bool last = (t == nt - 2);
;             const char* a1 = cA + (size_t)(t + 1) * kstep;
;             const char* a2 = last ? nA : cA + (size_t)(t + 2) * kstep; const char* b2 = last ? nB : cB + (size_t)(t + 2) * kstep;
;             const char* a3 = a2 + kstep; const char* b3 = b2 + kstep;
;     ...
; #pragma unroll
;         for (int a = 0; a < 2; ++a)
; #pragma unroll
;             for (int b = 0; b < 2; ++b)
; #pragma unroll
;                 for (int m = 0; m < 4; ++m)
; #pragma unroll
;                     for (int n = 0; n < 2; ++n) acc[a][b][m][n] = (f32x4){0.f, 0.f, 0.f, 0.f};
;         cur = nxt; cA = nA; cB = nB; ++ui;
.LBB0_327:
	s_ashr_i32 s7, s6, 31
	s_xor_b64 s[14:15], s[24:25], -1
	s_lshl_b64 s[12:13], s[6:7], 20
	s_add_u32 s12, s72, s12
	s_addc_u32 s13, s73, s13
	s_and_b64 s[16:17], s[24:25], exec
	s_cselect_b32 s7, s13, s21
	s_cselect_b32 s41, s12, s20
	s_ashr_i32 s11, s10, 31
	s_lshl_b64 s[16:17], s[10:11], 20
	v_readlane_b32 s42, v254, 5
	v_readlane_b32 s43, v254, 6
	s_add_u32 s16, s42, s16
	s_addc_u32 s17, s43, s17
	s_and_b64 s[24:25], s[24:25], exec
	s_cselect_b32 s11, s17, s23
	s_cselect_b32 s42, s16, s22
	s_add_u32 s20, s20, 0x80080
	s_addc_u32 s21, s21, 0
	s_add_u32 s43, s22, 0x100
	v_mov_b32_e32 v2, 0
	v_mov_b32_e32 v3, 0
	v_mov_b32_e32 v4, 0
	v_mov_b32_e32 v5, 0
	s_nop 1
	v_mfma_f32_16x16x32_bf16 v[6:9], v[2:5], v[2:5], 0
	v_mfma_f32_16x16x32_bf16 v[10:13], v[2:5], v[2:5], 0
	v_mfma_f32_16x16x32_bf16 v[14:17], v[2:5], v[2:5], 0
	v_mfma_f32_32x32x16_bf16 v[18:33], v[2:5], v[2:5], 0
	v_mfma_f32_32x32x16_bf16 v[34:49], v[2:5], v[2:5], 0
	v_mfma_f32_32x32x16_bf16 v[50:65], v[2:5], v[2:5], 0
	v_mfma_f32_32x32x16_bf16 v[66:81], v[2:5], v[2:5], 0
	v_mfma_f32_32x32x16_bf16 v[82:97], v[2:5], v[2:5], 0
	v_mfma_f32_32x32x16_bf16 v[98:113], v[2:5], v[2:5], 0
	v_mfma_f32_32x32x16_bf16 v[114:129], v[2:5], v[2:5], 0
	s_addc_u32 s44, s23, 0
	s_mov_b32 s45, -2

;     __device__ __forceinline__ const char* pa(const Unit& u) const { return (const char*)(A + (size_t)u.pm * a_tile_stride + (size_t)((u.pn >> a_group_shift) * a_group_cols)); }
;     __device__ __forceinline__ const char* pb(const Unit& u) const { return (const char*)(Bt + (size_t)u.pn * b_tile_stride); }
;     __device__ __forceinline__ const char* pa(const Unit& u) const { return (const char*)(A + (size_t)u.pm * a_tile_stride + (size_t)u.pn * 512); }
; template <class PT, class Epi>
; __device__ __forceinline__ void gemm_phase_once(LAS unsigned char* lds, const PT& S, const Epi& E, bool epi_on) {
;     ...
;         const bool has_next = S.next(ui + 1, nxt);
;         const char* nA = has_next ? S.pa(nxt) : cA; const char* nB = has_next ? S.pb(nxt) : cB;
;         for (int t = 0; t < nt; t += 2) {
;             const bool last = (t == nt - 2);
;             const char* a1 = cA + (size_t)(t + 1) * kstep;
;             const char* a2 = last ? nA : cA + (size_t)(t + 2) * kstep; const char* b2 = last ? nB : cB + (size_t)(t + 2) * kstep;
;             const char* a3 = a2 + kstep; const char* b3 = b2 + kstep;
;     ...
; #pragma unroll
;         for (int a = 0; a < 2; ++a)
; #pragma unroll
;             for (int b = 0; b < 2; ++b)
; #pragma unroll
;                 for (int m = 0; m < 4; ++m)
; #pragma unroll
;                     for (int n = 0; n < 2; ++n) acc[a][b][m][n] = (f32x4){0.f, 0.f, 0.f, 0.f};
;         cur = nxt; cA = nA; cB = nB; ++ui;
.LBB0_622:
	s_ashr_i32 s13, s12, 31
	s_lshl_b64 s[16:17], s[12:13], 21
	s_add_u32 s16, s92, s16
	s_addc_u32 s17, s93, s17
	s_and_b64 s[6:7], s[6:7], exec
	s_cselect_b32 s13, s17, s19
	s_cselect_b32 s38, s16, s18
	s_add_u32 s6, s20, 0x180080
	s_addc_u32 s7, s21, 0
	s_add_u32 s39, s18, 0x100
	v_mov_b32_e32 v2, 0
	v_mov_b32_e32 v3, 0
	v_mov_b32_e32 v4, 0
	v_mov_b32_e32 v5, 0
	s_nop 1
	v_mfma_f32_16x16x32_bf16 v[6:9], v[2:5], v[2:5], 0
	v_mfma_f32_16x16x32_bf16 v[10:13], v[2:5], v[2:5], 0
	v_mfma_f32_16x16x32_bf16 v[14:17], v[2:5], v[2:5], 0
	v_mfma_f32_32x32x16_bf16 v[18:33], v[2:5], v[2:5], 0
	v_mfma_f32_32x32x16_bf16 v[34:49], v[2:5], v[2:5], 0
	v_mfma_f32_32x32x16_bf16 v[50:65], v[2:5], v[2:5], 0
	v_mfma_f32_32x32x16_bf16 v[66:81], v[2:5], v[2:5], 0
	v_mfma_f32_32x32x16_bf16 v[82:97], v[2:5], v[2:5], 0
	v_mfma_f32_32x32x16_bf16 v[98:113], v[2:5], v[2:5], 0
	v_mfma_f32_32x32x16_bf16 v[114:129], v[2:5], v[2:5], 0
	s_addc_u32 s40, s19, 0
	s_mov_b32 s41, -2

;     __device__ __forceinline__ const char* pa(const Unit& u) const { return (const char*)(A + (size_t)u.pm * a_tile_stride + (size_t)((u.pn >> a_group_shift) * a_group_cols)); }
;     __device__ __forceinline__ const char* pb(const Unit& u) const { return (const char*)(Bt + (size_t)u.pn * b_tile_stride); }
;     __device__ __forceinline__ const char* pa(const Unit& u) const { return (const char*)(A + (size_t)u.pm * a_tile_stride + (size_t)u.pn * 512); }
; template <class PT, class Epi>
; __device__ __forceinline__ void gemm_phase_once(LAS unsigned char* lds, const PT& S, const Epi& E, bool epi_on) {
;     ...
;         const bool has_next = S.next(ui + 1, nxt);
;         const char* nA = has_next ? S.pa(nxt) : cA; const char* nB = has_next ? S.pb(nxt) : cB;
;         for (int t = 0; t < nt; t += 2) {
;             const bool last = (t == nt - 2);
;             const char* a1 = cA + (size_t)(t + 1) * kstep;
;             const char* a2 = last ? nA : cA + (size_t)(t + 2) * kstep; const char* b2 = last ? nB : cB + (size_t)(t + 2) * kstep;
;             const char* a3 = a2 + kstep; const char* b3 = b2 + kstep;
;     ...
; #pragma unroll
;         for (int a = 0; a < 2; ++a)
; #pragma unroll
;             for (int b = 0; b < 2; ++b)
; #pragma unroll
;                 for (int m = 0; m < 4; ++m)
; #pragma unroll
;                     for (int n = 0; n < 2; ++n) acc[a][b][m][n] = (f32x4){0.f, 0.f, 0.f, 0.f};
;         cur = nxt; cA = nA; cB = nB; ++ui;
.LBB0_756:
	s_ashr_i32 s11, s10, 31
	v_cmp_lt_i64_e32 vcc, s[12:13], v[142:143]
	s_lshl_b64 s[12:13], s[10:11], 20
	s_add_u32 s12, s72, s12
	s_addc_u32 s13, s73, s13
	s_and_b64 s[14:15], vcc, exec
	s_cselect_b32 s11, s13, s19
	s_cselect_b32 s39, s12, s18
	s_ashr_i32 s9, s8, 31
	s_lshl_b64 s[14:15], s[8:9], 20
	s_add_u32 s14, s84, s14
	s_addc_u32 s15, s85, s15
	s_and_b64 s[22:23], vcc, exec
	s_cselect_b32 s9, s15, s21
	s_cselect_b32 s40, s14, s20
	s_add_u32 s18, s18, 0x80080
	s_addc_u32 s19, s19, 0
	s_add_u32 s41, s20, 0x100
	v_mov_b32_e32 v2, 0
	v_mov_b32_e32 v3, 0
	v_mov_b32_e32 v4, 0
	v_mov_b32_e32 v5, 0
	s_nop 1
	v_mfma_f32_16x16x32_bf16 v[6:9], v[2:5], v[2:5], 0
	v_mfma_f32_16x16x32_bf16 v[10:13], v[2:5], v[2:5], 0
	v_mfma_f32_16x16x32_bf16 v[14:17], v[2:5], v[2:5], 0
	v_mfma_f32_32x32x16_bf16 v[18:33], v[2:5], v[2:5], 0
	v_mfma_f32_32x32x16_bf16 v[34:49], v[2:5], v[2:5], 0
	v_mfma_f32_32x32x16_bf16 v[50:65], v[2:5], v[2:5], 0
	v_mfma_f32_32x32x16_bf16 v[66:81], v[2:5], v[2:5], 0
	v_mfma_f32_32x32x16_bf16 v[82:97], v[2:5], v[2:5], 0
	v_mfma_f32_32x32x16_bf16 v[98:113], v[2:5], v[2:5], 0
	v_mfma_f32_32x32x16_bf16 v[114:129], v[2:5], v[2:5], 0
	s_addc_u32 s42, s21, 0
	s_mov_b32 s43, -2

;     __device__ __forceinline__ const char* pa(const Unit& u) const { return (const char*)(A + (size_t)u.pm * a_tile_stride + (size_t)((u.pn >> a_group_shift) * a_group_cols)); }
;     __device__ __forceinline__ const char* pb(const Unit& u) const { return (const char*)(Bt + (size_t)u.pn * b_tile_stride); }
;     __device__ __forceinline__ const char* pa(const Unit& u) const { return (const char*)(A + (size_t)u.pm * a_tile_stride + (size_t)u.pn * 512); }
; template <class PT, class Epi>
; __device__ __forceinline__ void gemm_phase_once(LAS unsigned char* lds, const PT& S, const Epi& E, bool epi_on) {
;     ...
;         const bool has_next = S.next(ui + 1, nxt);
;         const char* nA = has_next ? S.pa(nxt) : cA; const char* nB = has_next ? S.pb(nxt) : cB;
;         for (int t = 0; t < nt; t += 2) {
;             const bool last = (t == nt - 2);
;             const char* a1 = cA + (size_t)(t + 1) * kstep;
;             const char* a2 = last ? nA : cA + (size_t)(t + 2) * kstep; const char* b2 = last ? nB : cB + (size_t)(t + 2) * kstep;
;             const char* a3 = a2 + kstep; const char* b3 = b2 + kstep;
;     ...
; #pragma unroll
;         for (int a = 0; a < 2; ++a)
; #pragma unroll
;             for (int b = 0; b < 2; ++b)
; #pragma unroll
;                 for (int m = 0; m < 4; ++m)
; #pragma unroll
;                     for (int n = 0; n < 2; ++n) acc[a][b][m][n] = (f32x4){0.f, 0.f, 0.f, 0.f};
;         cur = nxt; cA = nA; cB = nB; ++ui;
.LBB0_779:
	s_ashr_i32 s13, s12, 31
	v_cmp_lt_i64_e64 s[24:25], s[14:15], 16
	s_lshl_b64 s[14:15], s[12:13], 20
	s_add_u32 s14, s81, s14
	s_addc_u32 s15, s96, s15
	s_and_b64 s[16:17], s[24:25], exec
	s_cselect_b32 s1, s15, s21
	s_cselect_b32 s13, s14, s20
	s_ashr_i32 s11, s10, 31
	s_lshl_b64 s[16:17], s[10:11], 20
	s_add_u32 s16, s82, s16
	s_addc_u32 s17, s83, s17
	s_and_b64 s[24:25], s[24:25], exec
	s_cselect_b32 s11, s17, s23
	s_cselect_b32 s19, s16, s22
	s_add_u32 s20, s20, 0x80080
	s_addc_u32 s21, s21, 0
	s_add_u32 s45, s22, 0x100
	v_mov_b32_e32 v2, 0
	v_mov_b32_e32 v3, 0
	v_mov_b32_e32 v4, 0
	v_mov_b32_e32 v5, 0
	s_nop 1
	v_mfma_f32_16x16x32_bf16 v[6:9], v[2:5], v[2:5], 0
	v_mfma_f32_16x16x32_bf16 v[10:13], v[2:5], v[2:5], 0
	v_mfma_f32_16x16x32_bf16 v[14:17], v[2:5], v[2:5], 0
	v_mfma_f32_32x32x16_bf16 v[18:33], v[2:5], v[2:5], 0
	v_mfma_f32_32x32x16_bf16 v[34:49], v[2:5], v[2:5], 0
	v_mfma_f32_32x32x16_bf16 v[50:65], v[2:5], v[2:5], 0
	v_mfma_f32_32x32x16_bf16 v[66:81], v[2:5], v[2:5], 0
	v_mfma_f32_32x32x16_bf16 v[82:97], v[2:5], v[2:5], 0
	v_mfma_f32_32x32x16_bf16 v[98:113], v[2:5], v[2:5], 0
	v_mfma_f32_32x32x16_bf16 v[114:129], v[2:5], v[2:5], 0
	s_addc_u32 s46, s23, 0
	s_mov_b32 s47, -2

;     __device__ __forceinline__ const char* pa(const Unit& u) const { return (const char*)(A + (size_t)u.pm * a_tile_stride + (size_t)((u.pn >> a_group_shift) * a_group_cols)); }
;     __device__ __forceinline__ const char* pb(const Unit& u) const { return (const char*)(Bt + (size_t)u.pn * b_tile_stride); }
;     __device__ __forceinline__ const char* pa(const Unit& u) const { return (const char*)(A + (size_t)u.pm * a_tile_stride + (size_t)u.pn * 512); }
; template <class PT, class Epi>
; __device__ __forceinline__ void gemm_phase_once(LAS unsigned char* lds, const PT& S, const Epi& E, bool epi_on) {
;     ...
;         const bool has_next = S.next(ui + 1, nxt);
;         const char* nA = has_next ? S.pa(nxt) : cA; const char* nB = has_next ? S.pb(nxt) : cB;
;         for (int t = 0; t < nt; t += 2) {
;             const bool last = (t == nt - 2);
;             const char* a1 = cA + (size_t)(t + 1) * kstep;
;             const char* a2 = last ? nA : cA + (size_t)(t + 2) * kstep; const char* b2 = last ? nB : cB + (size_t)(t + 2) * kstep;
;             const char* a3 = a2 + kstep; const char* b3 = b2 + kstep;
;     ...
; #pragma unroll
;         for (int a = 0; a < 2; ++a)
; #pragma unroll
;             for (int b = 0; b < 2; ++b)
; #pragma unroll
;                 for (int m = 0; m < 4; ++m)
; #pragma unroll
;                     for (int n = 0; n < 2; ++n) acc[a][b][m][n] = (f32x4){0.f, 0.f, 0.f, 0.f};
;         cur = nxt; cA = nA; cB = nB; ++ui;
.LBB0_1125:
	s_ashr_i32 s13, s12, 31
	v_cmp_lt_i64_e32 vcc, s[14:15], v[144:145]
	s_lshl_b64 s[14:15], s[12:13], 18
	v_readlane_b32 s16, v254, 48
	v_readlane_b32 s17, v254, 49
	s_add_u32 s14, s16, s14
	s_addc_u32 s15, s17, s15
	s_and_b64 s[16:17], vcc, exec
	s_cselect_b32 s13, s15, s19
	s_cselect_b32 s39, s14, s18
	s_ashr_i32 s9, s8, 31
	s_lshl_b64 s[16:17], s[8:9], 18
	v_readlane_b32 s22, v254, 7
	v_readlane_b32 s23, v254, 8
	s_add_u32 s16, s22, s16
	s_addc_u32 s17, s23, s17
	s_and_b64 s[22:23], vcc, exec
	s_cselect_b32 s9, s17, s21
	s_cselect_b32 s40, s16, s20
	s_add_u32 s18, s18, 0x20080
	s_addc_u32 s19, s19, 0
	s_add_u32 s41, s20, 0x100
	v_mov_b32_e32 v4, 0
	v_mov_b32_e32 v5, 0
	v_mov_b32_e32 v6, 0
	v_mov_b32_e32 v7, 0
	s_nop 1
	v_mfma_f32_16x16x32_bf16 v[8:11], v[4:7], v[4:7], 0
	v_mfma_f32_16x16x32_bf16 v[12:15], v[4:7], v[4:7], 0
	v_mfma_f32_16x16x32_bf16 v[16:19], v[4:7], v[4:7], 0
	v_mfma_f32_32x32x16_bf16 v[20:35], v[4:7], v[4:7], 0
	v_mfma_f32_32x32x16_bf16 v[36:51], v[4:7], v[4:7], 0
	v_mfma_f32_32x32x16_bf16 v[52:67], v[4:7], v[4:7], 0
	v_mfma_f32_32x32x16_bf16 v[68:83], v[4:7], v[4:7], 0
	v_mfma_f32_32x32x16_bf16 v[84:99], v[4:7], v[4:7], 0
	v_mfma_f32_32x32x16_bf16 v[100:115], v[4:7], v[4:7], 0
	v_mfma_f32_32x32x16_bf16 v[116:131], v[4:7], v[4:7], 0
	s_addc_u32 s42, s21, 0
	s_mov_b32 s43, -2

;     __device__ __forceinline__ const char* pa(const Unit& u) const { return (const char*)(A + (size_t)u.pm * a_tile_stride + (size_t)((u.pn >> a_group_shift) * a_group_cols)); }
;     __device__ __forceinline__ const char* pb(const Unit& u) const { return (const char*)(Bt + (size_t)u.pn * b_tile_stride); }
;     __device__ __forceinline__ const char* pa(const Unit& u) const { return (const char*)(A + (size_t)u.pm * a_tile_stride + (size_t)u.pn * 512); }
; template <class PT, class Epi>
; __device__ __forceinline__ void gemm_phase_once(LAS unsigned char* lds, const PT& S, const Epi& E, bool epi_on) {
;     ...
;         const bool has_next = S.next(ui + 1, nxt);
;         const char* nA = has_next ? S.pa(nxt) : cA; const char* nB = has_next ? S.pb(nxt) : cB;
;         for (int t = 0; t < nt; t += 2) {
;             const bool last = (t == nt - 2);
;             const char* a1 = cA + (size_t)(t + 1) * kstep;
;             const char* a2 = last ? nA : cA + (size_t)(t + 2) * kstep; const char* b2 = last ? nB : cB + (size_t)(t + 2) * kstep;
;             const char* a3 = a2 + kstep; const char* b3 = b2 + kstep;
;     ...
; #pragma unroll
;         for (int a = 0; a < 2; ++a)
; #pragma unroll
;             for (int b = 0; b < 2; ++b)
; #pragma unroll
;                 for (int m = 0; m < 4; ++m)
; #pragma unroll
;                     for (int n = 0; n < 2; ++n) acc[a][b][m][n] = (f32x4){0.f, 0.f, 0.f, 0.f};
;         cur = nxt; cA = nA; cB = nB; ++ui;
.LBB0_1252:
	s_ashr_i32 s23, s22, 31
	v_cmp_lt_i64_e32 vcc, s[24:25], v[154:155]
	s_lshl_b64 s[24:25], s[22:23], 20
	s_add_u32 s24, s72, s24
	s_addc_u32 s25, s73, s25
	s_and_b64 s[26:27], vcc, exec
	s_cselect_b32 s23, s25, s31
	s_cselect_b32 s29, s24, s30
	s_ashr_i32 s21, s20, 31
	s_lshl_b64 s[26:27], s[20:21], 20
	s_add_u32 s26, s76, s26
	s_addc_u32 s27, s77, s27
	s_and_b64 s[36:37], vcc, exec
	s_cselect_b32 s21, s27, s35
	s_cselect_b32 s58, s26, s34
	s_add_u32 s59, s34, 0x100
	v_mov_b32_e32 v4, 0
	v_mov_b32_e32 v5, 0
	v_mov_b32_e32 v6, 0
	v_mov_b32_e32 v7, 0
	s_nop 1
	v_mfma_f32_16x16x32_bf16 v[8:11], v[4:7], v[4:7], 0
	v_mfma_f32_16x16x32_bf16 v[12:15], v[4:7], v[4:7], 0
	v_mfma_f32_16x16x32_bf16 v[16:19], v[4:7], v[4:7], 0
	v_mfma_f32_32x32x16_bf16 v[20:35], v[4:7], v[4:7], 0
	v_mfma_f32_32x32x16_bf16 v[44:59], v[4:7], v[4:7], 0
	v_mfma_f32_32x32x16_bf16 v[60:75], v[4:7], v[4:7], 0
	v_mfma_f32_32x32x16_bf16 v[76:91], v[4:7], v[4:7], 0
	v_mfma_f32_32x32x16_bf16 v[92:107], v[4:7], v[4:7], 0
	v_mfma_f32_32x32x16_bf16 v[108:123], v[4:7], v[4:7], 0
	v_mfma_f32_32x32x16_bf16 v[124:139], v[4:7], v[4:7], 0
	s_addc_u32 s60, s35, 0
	s_mov_b32 s61, -2
	s_waitcnt lgkmcnt(0)
	s_waitcnt vmcnt(0)

;     __device__ __forceinline__ const char* pa(const Unit& u) const { return (const char*)(A + (size_t)u.pm * a_tile_stride + (size_t)((u.pn >> a_group_shift) * a_group_cols)); }
;     __device__ __forceinline__ const char* pb(const Unit& u) const { return (const char*)(Bt + (size_t)u.pn * b_tile_stride); }
;     __device__ __forceinline__ const char* pa(const Unit& u) const { return (const char*)(A + (size_t)u.pm * a_tile_stride + (size_t)u.pn * 512); }
; template <class PT, class Epi>
; __device__ __forceinline__ void gemm_phase_once(LAS unsigned char* lds, const PT& S, const Epi& E, bool epi_on) {
;     ...
;         const bool has_next = S.next(ui + 1, nxt);
;         const char* nA = has_next ? S.pa(nxt) : cA; const char* nB = has_next ? S.pb(nxt) : cB;
;         for (int t = 0; t < nt; t += 2) {
;             const bool last = (t == nt - 2);
;             const char* a1 = cA + (size_t)(t + 1) * kstep;
;             const char* a2 = last ? nA : cA + (size_t)(t + 2) * kstep; const char* b2 = last ? nB : cB + (size_t)(t + 2) * kstep;
;             const char* a3 = a2 + kstep; const char* b3 = b2 + kstep;
;     ...
; #pragma unroll
;         for (int a = 0; a < 2; ++a)
; #pragma unroll
;             for (int b = 0; b < 2; ++b)
; #pragma unroll
;                 for (int m = 0; m < 4; ++m)
; #pragma unroll
;                     for (int n = 0; n < 2; ++n) acc[a][b][m][n] = (f32x4){0.f, 0.f, 0.f, 0.f};
;         cur = nxt; cA = nA; cB = nB; ++ui;
.LBB0_1411:
	s_add_u32 s12, s12, 0x160080
	s_addc_u32 s13, s13, 0
	s_add_u32 s37, s14, 0x100
	v_mov_b32_e32 v4, 0
	v_mov_b32_e32 v5, 0
	v_mov_b32_e32 v6, 0
	v_mov_b32_e32 v7, 0
	s_nop 1
	v_mfma_f32_16x16x32_bf16 v[8:11], v[4:7], v[4:7], 0
	v_mfma_f32_16x16x32_bf16 v[12:15], v[4:7], v[4:7], 0
	v_mfma_f32_16x16x32_bf16 v[16:19], v[4:7], v[4:7], 0
	v_mfma_f32_32x32x16_bf16 v[20:35], v[4:7], v[4:7], 0
	v_mfma_f32_32x32x16_bf16 v[36:51], v[4:7], v[4:7], 0
	v_mfma_f32_32x32x16_bf16 v[52:67], v[4:7], v[4:7], 0
	v_mfma_f32_32x32x16_bf16 v[68:83], v[4:7], v[4:7], 0
	v_mfma_f32_32x32x16_bf16 v[84:99], v[4:7], v[4:7], 0
	v_mfma_f32_32x32x16_bf16 v[100:115], v[4:7], v[4:7], 0
	v_mfma_f32_32x32x16_bf16 v[116:131], v[4:7], v[4:7], 0
	s_addc_u32 s38, s15, 0
	s_mov_b32 s39, -2
	s_waitcnt lgkmcnt(0)

;     __device__ __forceinline__ const char* pa(const Unit& u) const { return (const char*)(A + (size_t)u.pm * a_tile_stride + (size_t)((u.pn >> a_group_shift) * a_group_cols)); }
;     __device__ __forceinline__ const char* pb(const Unit& u) const { return (const char*)(Bt + (size_t)u.pn * b_tile_stride); }
;     __device__ __forceinline__ const char* pa(const Unit& u) const { return (const char*)(A + (size_t)u.pm * a_tile_stride + (size_t)u.pn * 512); }
; template <class PT, class Epi>
; __device__ __forceinline__ void gemm_phase_once(LAS unsigned char* lds, const PT& S, const Epi& E, bool epi_on) {
;     ...
;         const bool has_next = S.next(ui + 1, nxt);
;         const char* nA = has_next ? S.pa(nxt) : cA; const char* nB = has_next ? S.pb(nxt) : cB;
;         for (int t = 0; t < nt; t += 2) {
;             const bool last = (t == nt - 2);
;             const char* a1 = cA + (size_t)(t + 1) * kstep;
;             const char* a2 = last ? nA : cA + (size_t)(t + 2) * kstep; const char* b2 = last ? nB : cB + (size_t)(t + 2) * kstep;
;             const char* a3 = a2 + kstep; const char* b3 = b2 + kstep;
;     ...
; #pragma unroll
;         for (int a = 0; a < 2; ++a)
; #pragma unroll
;             for (int b = 0; b < 2; ++b)
; #pragma unroll
;                 for (int m = 0; m < 4; ++m)
; #pragma unroll
;                     for (int n = 0; n < 2; ++n) acc[a][b][m][n] = (f32x4){0.f, 0.f, 0.f, 0.f};
;         cur = nxt; cA = nA; cB = nB; ++ui;
.LBB0_1734:
	s_ashr_i32 s15, s14, 31
	s_xor_b64 s[24:25], s[0:1], -1
	s_lshl_b64 s[22:23], s[14:15], 20
	s_add_u32 s22, s72, s22
	s_addc_u32 s23, s73, s23
	s_and_b64 s[26:27], s[0:1], exec
	s_cselect_b32 s3, s23, s31
	s_cselect_b32 s15, s22, s30
	s_ashr_i32 s21, s20, 31
	s_lshl_b64 s[26:27], s[20:21], 20
	v_readlane_b32 s34, v254, 5
	v_readlane_b32 s35, v254, 6
	s_add_u32 s26, s34, s26
	s_addc_u32 s27, s35, s27
	s_and_b64 s[0:1], s[0:1], exec
	s_cselect_b32 s21, s27, s29
	s_cselect_b32 s34, s26, s28
	s_add_u32 s0, s30, 0x80080
	s_addc_u32 s1, s31, 0
	s_add_u32 s35, s28, 0x100
	v_mov_b32_e32 v4, 0
	v_mov_b32_e32 v5, 0
	v_mov_b32_e32 v6, 0
	v_mov_b32_e32 v7, 0
	s_nop 1
	v_mfma_f32_16x16x32_bf16 v[8:11], v[4:7], v[4:7], 0
	v_mfma_f32_16x16x32_bf16 v[12:15], v[4:7], v[4:7], 0
	v_mfma_f32_16x16x32_bf16 v[16:19], v[4:7], v[4:7], 0
	v_mfma_f32_32x32x16_bf16 v[20:35], v[4:7], v[4:7], 0
	v_mfma_f32_32x32x16_bf16 v[36:51], v[4:7], v[4:7], 0
	v_mfma_f32_32x32x16_bf16 v[52:67], v[4:7], v[4:7], 0
	v_mfma_f32_32x32x16_bf16 v[68:83], v[4:7], v[4:7], 0
	v_mfma_f32_32x32x16_bf16 v[84:99], v[4:7], v[4:7], 0
	v_mfma_f32_32x32x16_bf16 v[100:115], v[4:7], v[4:7], 0
	v_mfma_f32_32x32x16_bf16 v[116:131], v[4:7], v[4:7], 0
	s_addc_u32 s53, s29, 0
	s_mov_b32 s56, -2
	s_waitcnt lgkmcnt(0)
	s_waitcnt vmcnt(0)

;     __device__ __forceinline__ const char* pa(const Unit& u) const { return (const char*)(A + (size_t)u.pm * a_tile_stride + (size_t)((u.pn >> a_group_shift) * a_group_cols)); }
;     __device__ __forceinline__ const char* pb(const Unit& u) const { return (const char*)(Bt + (size_t)u.pn * b_tile_stride); }
;     __device__ __forceinline__ const char* pa(const Unit& u) const { return (const char*)(A + (size_t)u.pm * a_tile_stride + (size_t)u.pn * 512); }
; template <class PT, class Epi>
; __device__ __forceinline__ void gemm_phase_once(LAS unsigned char* lds, const PT& S, const Epi& E, bool epi_on) {
;     ...
;         const bool has_next = S.next(ui + 1, nxt);
;         const char* nA = has_next ? S.pa(nxt) : cA; const char* nB = has_next ? S.pb(nxt) : cB;
;         for (int t = 0; t < nt; t += 2) {
;             const bool last = (t == nt - 2);
;             const char* a1 = cA + (size_t)(t + 1) * kstep;
;             const char* a2 = last ? nA : cA + (size_t)(t + 2) * kstep; const char* b2 = last ? nB : cB + (size_t)(t + 2) * kstep;
;             const char* a3 = a2 + kstep; const char* b3 = b2 + kstep;
;     ...
; #pragma unroll
;         for (int a = 0; a < 2; ++a)
; #pragma unroll
;             for (int b = 0; b < 2; ++b)
; #pragma unroll
;                 for (int m = 0; m < 4; ++m)
; #pragma unroll
;                     for (int n = 0; n < 2; ++n) acc[a][b][m][n] = (f32x4){0.f, 0.f, 0.f, 0.f};
;         cur = nxt; cA = nA; cB = nB; ++ui;
.LBB0_1956:
	s_ashr_i32 s46, s22, 4
	s_ashr_i32 s47, s46, 31
	s_lshl_b64 s[46:47], s[46:47], 21
	v_readlane_b32 s48, v254, 52
	v_readlane_b32 s49, v254, 53
	s_add_u32 s21, s48, s46
	s_addc_u32 s23, s49, s47
	s_add_u32 s24, s21, s24
	s_addc_u32 s25, s23, s25
	s_and_b64 s[6:7], s[6:7], exec
	s_cselect_b32 s21, s25, s27
	s_cselect_b32 s23, s24, s26
	s_add_u32 s6, s28, 0x80080
	s_addc_u32 s7, s29, 0
	s_add_u32 s45, s26, 0x100
	v_mov_b32_e32 v4, 0
	v_mov_b32_e32 v5, 0
	v_mov_b32_e32 v6, 0
	v_mov_b32_e32 v7, 0
	s_nop 1
	v_mfma_f32_16x16x32_bf16 v[8:11], v[4:7], v[4:7], 0
	v_mfma_f32_16x16x32_bf16 v[12:15], v[4:7], v[4:7], 0
	v_mfma_f32_16x16x32_bf16 v[16:19], v[4:7], v[4:7], 0
	v_mfma_f32_32x32x16_bf16 v[20:35], v[4:7], v[4:7], 0
	v_mfma_f32_32x32x16_bf16 v[36:51], v[4:7], v[4:7], 0
	v_mfma_f32_32x32x16_bf16 v[52:67], v[4:7], v[4:7], 0
	v_mfma_f32_32x32x16_bf16 v[68:83], v[4:7], v[4:7], 0
	v_mfma_f32_32x32x16_bf16 v[84:99], v[4:7], v[4:7], 0
	v_mfma_f32_32x32x16_bf16 v[100:115], v[4:7], v[4:7], 0
	v_mfma_f32_32x32x16_bf16 v[116:131], v[4:7], v[4:7], 0
	s_addc_u32 s46, s27, 0
	s_mov_b32 s47, -2
	s_waitcnt lgkmcnt(0)

;     __device__ __forceinline__ const char* pa(const Unit& u) const { return (const char*)(A + (size_t)u.pm * a_tile_stride + (size_t)((u.pn >> a_group_shift) * a_group_cols)); }
;     __device__ __forceinline__ const char* pb(const Unit& u) const { return (const char*)(Bt + (size_t)u.pn * b_tile_stride); }
;     __device__ __forceinline__ const char* pa(const Unit& u) const { return (const char*)(A + (size_t)u.pm * a_tile_stride + (size_t)u.pn * 512); }
; template <class PT, class Epi>
; __device__ __forceinline__ void gemm_phase_once(LAS unsigned char* lds, const PT& S, const Epi& E, bool epi_on) {
;     ...
;         const bool has_next = S.next(ui + 1, nxt);
;         const char* nA = has_next ? S.pa(nxt) : cA; const char* nB = has_next ? S.pb(nxt) : cB;
;         for (int t = 0; t < nt; t += 2) {
;             const bool last = (t == nt - 2);
;             const char* a1 = cA + (size_t)(t + 1) * kstep;
;             const char* a2 = last ? nA : cA + (size_t)(t + 2) * kstep; const char* b2 = last ? nB : cB + (size_t)(t + 2) * kstep;
;             const char* a3 = a2 + kstep; const char* b3 = b2 + kstep;
;     ...
; #pragma unroll
;         for (int a = 0; a < 2; ++a)
; #pragma unroll
;             for (int b = 0; b < 2; ++b)
; #pragma unroll
;                 for (int m = 0; m < 4; ++m)
; #pragma unroll
;                     for (int n = 0; n < 2; ++n) acc[a][b][m][n] = (f32x4){0.f, 0.f, 0.f, 0.f};
;         cur = nxt; cA = nA; cB = nB; ++ui;
.LBB0_2421:
	s_ashr_i32 s15, s14, 31
	v_cmp_lt_i64_e32 vcc, s[16:17], v[144:145]
	s_lshl_b64 s[16:17], s[14:15], 20
	s_add_u32 s16, s78, s16
	s_addc_u32 s17, s79, s17
	s_and_b64 s[18:19], vcc, exec
	s_cselect_b32 s15, s17, s21
	s_cselect_b32 s41, s16, s20
	s_ashr_i32 s11, s10, 31
	s_lshl_b64 s[18:19], s[10:11], 20
	s_add_u32 s18, s92, s18
	s_addc_u32 s19, s93, s19
	s_and_b64 s[24:25], vcc, exec
	s_cselect_b32 s11, s19, s23
	s_cselect_b32 s42, s18, s22
	s_add_u32 s20, s20, 0x80080
	s_addc_u32 s21, s21, 0
	s_add_u32 s43, s22, 0x100
	v_mov_b32_e32 v4, 0
	v_mov_b32_e32 v5, 0
	v_mov_b32_e32 v6, 0
	v_mov_b32_e32 v7, 0
	s_nop 1
	v_mfma_f32_16x16x32_bf16 v[8:11], v[4:7], v[4:7], 0
	v_mfma_f32_16x16x32_bf16 v[12:15], v[4:7], v[4:7], 0
	v_mfma_f32_16x16x32_bf16 v[16:19], v[4:7], v[4:7], 0
	v_mfma_f32_32x32x16_bf16 v[20:35], v[4:7], v[4:7], 0
	v_mfma_f32_32x32x16_bf16 v[36:51], v[4:7], v[4:7], 0
	v_mfma_f32_32x32x16_bf16 v[52:67], v[4:7], v[4:7], 0
	v_mfma_f32_32x32x16_bf16 v[68:83], v[4:7], v[4:7], 0
	v_mfma_f32_32x32x16_bf16 v[84:99], v[4:7], v[4:7], 0
	v_mfma_f32_32x32x16_bf16 v[100:115], v[4:7], v[4:7], 0
	v_mfma_f32_32x32x16_bf16 v[116:131], v[4:7], v[4:7], 0
	s_addc_u32 s44, s23, 0
	s_mov_b32 s45, -2
	s_waitcnt lgkmcnt(0)

;     __device__ __forceinline__ const char* pa(const Unit& u) const { return (const char*)(A + (size_t)u.pm * a_tile_stride + (size_t)((u.pn >> a_group_shift) * a_group_cols)); }
;     __device__ __forceinline__ const char* pb(const Unit& u) const { return (const char*)(Bt + (size_t)u.pn * b_tile_stride); }
;     __device__ __forceinline__ const char* pa(const Unit& u) const { return (const char*)(A + (size_t)u.pm * a_tile_stride + (size_t)u.pn * 512); }
; template <class PT, class Epi>
; __device__ __forceinline__ void gemm_phase_once(LAS unsigned char* lds, const PT& S, const Epi& E, bool epi_on) {
;     ...
;         const bool has_next = S.next(ui + 1, nxt);
;         const char* nA = has_next ? S.pa(nxt) : cA; const char* nB = has_next ? S.pb(nxt) : cB;
;         for (int t = 0; t < nt; t += 2) {
;             const bool last = (t == nt - 2);
;             const char* a1 = cA + (size_t)(t + 1) * kstep;
;             const char* a2 = last ? nA : cA + (size_t)(t + 2) * kstep; const char* b2 = last ? nB : cB + (size_t)(t + 2) * kstep;
;             const char* a3 = a2 + kstep; const char* b3 = b2 + kstep;
;     ...
; #pragma unroll
;         for (int a = 0; a < 2; ++a)
; #pragma unroll
;             for (int b = 0; b < 2; ++b)
; #pragma unroll
;                 for (int m = 0; m < 4; ++m)
; #pragma unroll
;                     for (int n = 0; n < 2; ++n) acc[a][b][m][n] = (f32x4){0.f, 0.f, 0.f, 0.f};
;         cur = nxt; cA = nA; cB = nB; ++ui;
.LBB0_2555:
	s_ashr_i32 s13, s12, 31
	v_cmp_lt_i64_e32 vcc, s[14:15], v[144:145]
	s_lshl_b64 s[14:15], s[12:13], 20
	s_add_u32 s14, s72, s14
	s_addc_u32 s15, s73, s15
	s_and_b64 s[16:17], vcc, exec
	s_cselect_b32 s13, s15, s21
	s_cselect_b32 s41, s14, s20
	s_ashr_i32 s11, s10, 31
	s_lshl_b64 s[16:17], s[10:11], 20
	s_add_u32 s16, s84, s16
	s_addc_u32 s17, s85, s17
	s_and_b64 s[24:25], vcc, exec
	s_cselect_b32 s11, s17, s23
	s_cselect_b32 s42, s16, s22
	s_add_u32 s20, s20, 0x80080
	s_addc_u32 s21, s21, 0
	s_add_u32 s43, s22, 0x100
	v_mov_b32_e32 v4, 0
	v_mov_b32_e32 v5, 0
	v_mov_b32_e32 v6, 0
	v_mov_b32_e32 v7, 0
	s_nop 1
	v_mfma_f32_16x16x32_bf16 v[8:11], v[4:7], v[4:7], 0
	v_mfma_f32_16x16x32_bf16 v[12:15], v[4:7], v[4:7], 0
	v_mfma_f32_16x16x32_bf16 v[16:19], v[4:7], v[4:7], 0
	v_mfma_f32_32x32x16_bf16 v[20:35], v[4:7], v[4:7], 0
	v_mfma_f32_32x32x16_bf16 v[36:51], v[4:7], v[4:7], 0
	v_mfma_f32_32x32x16_bf16 v[52:67], v[4:7], v[4:7], 0
	v_mfma_f32_32x32x16_bf16 v[68:83], v[4:7], v[4:7], 0
	v_mfma_f32_32x32x16_bf16 v[84:99], v[4:7], v[4:7], 0
	v_mfma_f32_32x32x16_bf16 v[100:115], v[4:7], v[4:7], 0
	v_mfma_f32_32x32x16_bf16 v[116:131], v[4:7], v[4:7], 0
	s_addc_u32 s44, s23, 0
	s_mov_b32 s45, -2
	s_waitcnt lgkmcnt(0)
	s_waitcnt vmcnt(0)

;     __device__ __forceinline__ const char* pa(const Unit& u) const { return (const char*)(A + (size_t)u.pm * a_tile_stride + (size_t)((u.pn >> a_group_shift) * a_group_cols)); }
;     __device__ __forceinline__ const char* pb(const Unit& u) const { return (const char*)(Bt + (size_t)u.pn * b_tile_stride); }
;     __device__ __forceinline__ const char* pa(const Unit& u) const { return (const char*)(A + (size_t)u.pm * a_tile_stride + (size_t)u.pn * 512); }
; template <class PT, class Epi>
; __device__ __forceinline__ void gemm_phase_once(LAS unsigned char* lds, const PT& S, const Epi& E, bool epi_on) {
;     ...
;         const bool has_next = S.next(ui + 1, nxt);
;         const char* nA = has_next ? S.pa(nxt) : cA; const char* nB = has_next ? S.pb(nxt) : cB;
;         for (int t = 0; t < nt; t += 2) {
;             const bool last = (t == nt - 2);
;             const char* a1 = cA + (size_t)(t + 1) * kstep;
;             const char* a2 = last ? nA : cA + (size_t)(t + 2) * kstep; const char* b2 = last ? nB : cB + (size_t)(t + 2) * kstep;
;             const char* a3 = a2 + kstep; const char* b3 = b2 + kstep;
;     ...
; #pragma unroll
;         for (int a = 0; a < 2; ++a)
; #pragma unroll
;             for (int b = 0; b < 2; ++b)
; #pragma unroll
;                 for (int m = 0; m < 4; ++m)
; #pragma unroll
;                     for (int n = 0; n < 2; ++n) acc[a][b][m][n] = (f32x4){0.f, 0.f, 0.f, 0.f};
;         cur = nxt; cA = nA; cB = nB; ++ui;
.LBB0_2578:
	s_ashr_i32 s15, s14, 31
	v_cmp_lt_i64_e64 s[26:27], s[16:17], 16
	s_lshl_b64 s[16:17], s[14:15], 20
	s_add_u32 s16, s81, s16
	s_addc_u32 s17, s96, s17
	s_and_b64 s[18:19], s[26:27], exec
	s_cselect_b32 s1, s17, s23
	s_cselect_b32 s15, s16, s22
	s_ashr_i32 s13, s12, 31
	s_lshl_b64 s[18:19], s[12:13], 20
	s_add_u32 s18, s82, s18
	s_addc_u32 s19, s83, s19
	s_and_b64 s[26:27], s[26:27], exec
	s_cselect_b32 s13, s19, s25
	s_cselect_b32 s21, s18, s24
	s_add_u32 s22, s22, 0x80080
	s_addc_u32 s23, s23, 0
	s_add_u32 s47, s24, 0x100
	v_mov_b32_e32 v4, 0
	v_mov_b32_e32 v5, 0
	v_mov_b32_e32 v6, 0
	v_mov_b32_e32 v7, 0
	s_nop 1
	v_mfma_f32_16x16x32_bf16 v[8:11], v[4:7], v[4:7], 0
	v_mfma_f32_16x16x32_bf16 v[12:15], v[4:7], v[4:7], 0
	v_mfma_f32_16x16x32_bf16 v[16:19], v[4:7], v[4:7], 0
	v_mfma_f32_32x32x16_bf16 v[20:35], v[4:7], v[4:7], 0
	v_mfma_f32_32x32x16_bf16 v[36:51], v[4:7], v[4:7], 0
	v_mfma_f32_32x32x16_bf16 v[52:67], v[4:7], v[4:7], 0
	v_mfma_f32_32x32x16_bf16 v[68:83], v[4:7], v[4:7], 0
	v_mfma_f32_32x32x16_bf16 v[84:99], v[4:7], v[4:7], 0
	v_mfma_f32_32x32x16_bf16 v[100:115], v[4:7], v[4:7], 0
	v_mfma_f32_32x32x16_bf16 v[116:131], v[4:7], v[4:7], 0
	s_addc_u32 s48, s25, 0
	s_mov_b32 s49, -2
	s_waitcnt lgkmcnt(0)

;     __device__ __forceinline__ const char* pa(const Unit& u) const { return (const char*)(A + (size_t)u.pm * a_tile_stride + (size_t)((u.pn >> a_group_shift) * a_group_cols)); }
;     __device__ __forceinline__ const char* pb(const Unit& u) const { return (const char*)(Bt + (size_t)u.pn * b_tile_stride); }
;     __device__ __forceinline__ const char* pa(const Unit& u) const { return (const char*)(A + (size_t)u.pm * a_tile_stride + (size_t)u.pn * 512); }
; template <class PT, class Epi>
; __device__ __forceinline__ void gemm_phase_once(LAS unsigned char* lds, const PT& S, const Epi& E, bool epi_on) {
;     ...
;         const bool has_next = S.next(ui + 1, nxt);
;         const char* nA = has_next ? S.pa(nxt) : cA; const char* nB = has_next ? S.pb(nxt) : cB;
;         for (int t = 0; t < nt; t += 2) {
;             const bool last = (t == nt - 2);
;             const char* a1 = cA + (size_t)(t + 1) * kstep;
;             const char* a2 = last ? nA : cA + (size_t)(t + 2) * kstep; const char* b2 = last ? nB : cB + (size_t)(t + 2) * kstep;
;             const char* a3 = a2 + kstep; const char* b3 = b2 + kstep;
;     ...
; #pragma unroll
;         for (int a = 0; a < 2; ++a)
; #pragma unroll
;             for (int b = 0; b < 2; ++b)
; #pragma unroll
;                 for (int m = 0; m < 4; ++m)
; #pragma unroll
;                     for (int n = 0; n < 2; ++n) acc[a][b][m][n] = (f32x4){0.f, 0.f, 0.f, 0.f};
;         cur = nxt; cA = nA; cB = nB; ++ui;
.LBB0_2855:
	s_ashr_i32 s15, s14, 31
	v_cmp_lt_i64_e32 vcc, s[16:17], v[144:145]
	s_lshl_b64 s[16:17], s[14:15], 18
	v_readlane_b32 s18, v254, 48
	v_readlane_b32 s19, v254, 49
	s_add_u32 s16, s18, s16
	s_addc_u32 s17, s19, s17
	s_and_b64 s[18:19], vcc, exec
	s_cselect_b32 s15, s17, s21
	s_cselect_b32 s41, s16, s20
	s_ashr_i32 s11, s10, 31
	s_lshl_b64 s[18:19], s[10:11], 18
	v_readlane_b32 s24, v254, 7
	v_readlane_b32 s25, v254, 8
	s_add_u32 s18, s24, s18
	s_addc_u32 s19, s25, s19
	s_and_b64 s[24:25], vcc, exec
	s_cselect_b32 s11, s19, s23
	s_cselect_b32 s42, s18, s22
	s_add_u32 s20, s20, 0x20080
	s_addc_u32 s21, s21, 0
	s_add_u32 s43, s22, 0x100
	v_mov_b32_e32 v4, 0
	v_mov_b32_e32 v5, 0
	v_mov_b32_e32 v6, 0
	v_mov_b32_e32 v7, 0
	s_nop 1
	v_mfma_f32_16x16x32_bf16 v[8:11], v[4:7], v[4:7], 0
	v_mfma_f32_16x16x32_bf16 v[12:15], v[4:7], v[4:7], 0
	v_mfma_f32_16x16x32_bf16 v[16:19], v[4:7], v[4:7], 0
	v_mfma_f32_32x32x16_bf16 v[20:35], v[4:7], v[4:7], 0
	v_mfma_f32_32x32x16_bf16 v[36:51], v[4:7], v[4:7], 0
	v_mfma_f32_32x32x16_bf16 v[52:67], v[4:7], v[4:7], 0
	v_mfma_f32_32x32x16_bf16 v[68:83], v[4:7], v[4:7], 0
	v_mfma_f32_32x32x16_bf16 v[84:99], v[4:7], v[4:7], 0
	v_mfma_f32_32x32x16_bf16 v[100:115], v[4:7], v[4:7], 0
	v_mfma_f32_32x32x16_bf16 v[116:131], v[4:7], v[4:7], 0
	s_addc_u32 s44, s23, 0
	s_mov_b32 s45, -2
	s_waitcnt lgkmcnt(0)

;     __device__ __forceinline__ const char* pa(const Unit& u) const { return (const char*)(A + (size_t)u.pm * a_tile_stride + (size_t)((u.pn >> a_group_shift) * a_group_cols)); }
;     __device__ __forceinline__ const char* pb(const Unit& u) const { return (const char*)(Bt + (size_t)u.pn * b_tile_stride); }
;     __device__ __forceinline__ const char* pa(const Unit& u) const { return (const char*)(A + (size_t)u.pm * a_tile_stride + (size_t)u.pn * 512); }
; template <class PT, class Epi>
; __device__ __forceinline__ void gemm_phase_once(LAS unsigned char* lds, const PT& S, const Epi& E, bool epi_on) {
;     ...
;         const bool has_next = S.next(ui + 1, nxt);
;         const char* nA = has_next ? S.pa(nxt) : cA; const char* nB = has_next ? S.pb(nxt) : cB;
;         for (int t = 0; t < nt; t += 2) {
;             const bool last = (t == nt - 2);
;             const char* a1 = cA + (size_t)(t + 1) * kstep;
;             const char* a2 = last ? nA : cA + (size_t)(t + 2) * kstep; const char* b2 = last ? nB : cB + (size_t)(t + 2) * kstep;
;             const char* a3 = a2 + kstep; const char* b3 = b2 + kstep;
;     ...
; #pragma unroll
;         for (int a = 0; a < 2; ++a)
; #pragma unroll
;             for (int b = 0; b < 2; ++b)
; #pragma unroll
;                 for (int m = 0; m < 4; ++m)
; #pragma unroll
;                     for (int n = 0; n < 2; ++n) acc[a][b][m][n] = (f32x4){0.f, 0.f, 0.f, 0.f};
;         cur = nxt; cA = nA; cB = nB; ++ui;
.LBB0_2982:
	s_ashr_i32 s29, s28, 31
	v_cmp_lt_i64_e32 vcc, s[30:31], v[154:155]
	s_lshl_b64 s[30:31], s[28:29], 20
	s_add_u32 s30, s72, s30
	s_addc_u32 s31, s73, s31
	s_and_b64 s[34:35], vcc, exec
	s_cselect_b32 s29, s31, s39
	s_cselect_b32 s37, s30, s38
	s_ashr_i32 s27, s26, 31
	s_lshl_b64 s[34:35], s[26:27], 20
	s_add_u32 s34, s76, s34
	s_addc_u32 s35, s77, s35
	s_and_b64 s[42:43], vcc, exec
	s_cselect_b32 s27, s35, s41
	s_cselect_b32 s64, s34, s40
	s_add_u32 s65, s40, 0x100
	v_mov_b32_e32 v4, 0
	v_mov_b32_e32 v5, 0
	v_mov_b32_e32 v6, 0
	v_mov_b32_e32 v7, 0
	s_nop 1
	v_mfma_f32_16x16x32_bf16 v[8:11], v[4:7], v[4:7], 0
	v_mfma_f32_16x16x32_bf16 v[12:15], v[4:7], v[4:7], 0
	v_mfma_f32_16x16x32_bf16 v[16:19], v[4:7], v[4:7], 0
	v_mfma_f32_32x32x16_bf16 v[20:35], v[4:7], v[4:7], 0
	v_mfma_f32_32x32x16_bf16 v[44:59], v[4:7], v[4:7], 0
	v_mfma_f32_32x32x16_bf16 v[60:75], v[4:7], v[4:7], 0
	v_mfma_f32_32x32x16_bf16 v[76:91], v[4:7], v[4:7], 0
	v_mfma_f32_32x32x16_bf16 v[92:107], v[4:7], v[4:7], 0
	v_mfma_f32_32x32x16_bf16 v[108:123], v[4:7], v[4:7], 0
	v_mfma_f32_32x32x16_bf16 v[124:139], v[4:7], v[4:7], 0
	s_addc_u32 s66, s41, 0
	s_mov_b32 s67, -2
	s_waitcnt lgkmcnt(0)
	s_waitcnt vmcnt(0)

;     __device__ __forceinline__ const char* pa(const Unit& u) const { return (const char*)(A + (size_t)u.pm * a_tile_stride + (size_t)((u.pn >> a_group_shift) * a_group_cols)); }
;     __device__ __forceinline__ const char* pb(const Unit& u) const { return (const char*)(Bt + (size_t)u.pn * b_tile_stride); }
;     __device__ __forceinline__ const char* pa(const Unit& u) const { return (const char*)(A + (size_t)u.pm * a_tile_stride + (size_t)u.pn * 512); }
; template <class PT, class Epi>
; __device__ __forceinline__ void gemm_phase_once(LAS unsigned char* lds, const PT& S, const Epi& E, bool epi_on) {
;     ...
;         const bool has_next = S.next(ui + 1, nxt);
;         const char* nA = has_next ? S.pa(nxt) : cA; const char* nB = has_next ? S.pb(nxt) : cB;
;         for (int t = 0; t < nt; t += 2) {
;             const bool last = (t == nt - 2);
;             const char* a1 = cA + (size_t)(t + 1) * kstep;
;             const char* a2 = last ? nA : cA + (size_t)(t + 2) * kstep; const char* b2 = last ? nB : cB + (size_t)(t + 2) * kstep;
;             const char* a3 = a2 + kstep; const char* b3 = b2 + kstep;
;     ...
; #pragma unroll
;         for (int a = 0; a < 2; ++a)
; #pragma unroll
;             for (int b = 0; b < 2; ++b)
; #pragma unroll
;                 for (int m = 0; m < 4; ++m)
; #pragma unroll
;                     for (int n = 0; n < 2; ++n) acc[a][b][m][n] = (f32x4){0.f, 0.f, 0.f, 0.f};
;         cur = nxt; cA = nA; cB = nB; ++ui;
.LBB0_3141:
	s_add_u32 s14, s14, 0x160080
	s_addc_u32 s15, s15, 0
	s_add_u32 s39, s16, 0x100
	v_mov_b32_e32 v4, 0
	v_mov_b32_e32 v5, 0
	v_mov_b32_e32 v6, 0
	v_mov_b32_e32 v7, 0
	s_nop 1
	v_mfma_f32_16x16x32_bf16 v[8:11], v[4:7], v[4:7], 0
	v_mfma_f32_16x16x32_bf16 v[12:15], v[4:7], v[4:7], 0
	v_mfma_f32_16x16x32_bf16 v[16:19], v[4:7], v[4:7], 0
	v_mfma_f32_32x32x16_bf16 v[20:35], v[4:7], v[4:7], 0
	v_mfma_f32_32x32x16_bf16 v[36:51], v[4:7], v[4:7], 0
	v_mfma_f32_32x32x16_bf16 v[52:67], v[4:7], v[4:7], 0
	v_mfma_f32_32x32x16_bf16 v[68:83], v[4:7], v[4:7], 0
	v_mfma_f32_32x32x16_bf16 v[84:99], v[4:7], v[4:7], 0
	v_mfma_f32_32x32x16_bf16 v[100:115], v[4:7], v[4:7], 0
	v_mfma_f32_32x32x16_bf16 v[116:131], v[4:7], v[4:7], 0
	s_addc_u32 s40, s17, 0
	s_mov_b32 s41, -2
	s_waitcnt lgkmcnt(0)

;     __device__ __forceinline__ const char* pa(const Unit& u) const { return (const char*)(A + (size_t)u.pm * a_tile_stride + (size_t)((u.pn >> a_group_shift) * a_group_cols)); }
;     __device__ __forceinline__ const char* pb(const Unit& u) const { return (const char*)(Bt + (size_t)u.pn * b_tile_stride); }
;     __device__ __forceinline__ const char* pa(const Unit& u) const { return (const char*)(A + (size_t)u.pm * a_tile_stride + (size_t)u.pn * 512); }
; template <class PT, class Epi>
; __device__ __forceinline__ void gemm_phase_once(LAS unsigned char* lds, const PT& S, const Epi& E, bool epi_on) {
;     ...
;         const bool has_next = S.next(ui + 1, nxt);
;         const char* nA = has_next ? S.pa(nxt) : cA; const char* nB = has_next ? S.pb(nxt) : cB;
;         for (int t = 0; t < nt; t += 2) {
;             const bool last = (t == nt - 2);
;             const char* a1 = cA + (size_t)(t + 1) * kstep;
;             const char* a2 = last ? nA : cA + (size_t)(t + 2) * kstep; const char* b2 = last ? nB : cB + (size_t)(t + 2) * kstep;
;             const char* a3 = a2 + kstep; const char* b3 = b2 + kstep;
;     ...
; #pragma unroll
;         for (int a = 0; a < 2; ++a)
; #pragma unroll
;             for (int b = 0; b < 2; ++b)
; #pragma unroll
;                 for (int m = 0; m < 4; ++m)
; #pragma unroll
;                     for (int n = 0; n < 2; ++n) acc[a][b][m][n] = (f32x4){0.f, 0.f, 0.f, 0.f};
;         cur = nxt; cA = nA; cB = nB; ++ui;
.LBB0_3457:
	s_ashr_i32 s9, s8, 31
	s_xor_b64 s[14:15], s[24:25], -1
	s_lshl_b64 s[12:13], s[8:9], 20
	s_add_u32 s12, s72, s12
	s_addc_u32 s13, s73, s13
	s_and_b64 s[16:17], s[24:25], exec
	s_cselect_b32 s9, s13, s21
	s_cselect_b32 s41, s12, s20
	s_ashr_i32 s11, s10, 31
	s_lshl_b64 s[16:17], s[10:11], 20
	v_readlane_b32 s42, v254, 5
	v_readlane_b32 s43, v254, 6
	s_add_u32 s16, s42, s16
	s_addc_u32 s17, s43, s17
	s_and_b64 s[24:25], s[24:25], exec
	s_cselect_b32 s11, s17, s23
	s_cselect_b32 s42, s16, s22
	s_add_u32 s20, s20, 0x80080
	s_addc_u32 s21, s21, 0
	s_add_u32 s43, s22, 0x100
	v_mov_b32_e32 v4, 0
	v_mov_b32_e32 v5, 0
	v_mov_b32_e32 v6, 0
	v_mov_b32_e32 v7, 0
	s_nop 1
	v_mfma_f32_16x16x32_bf16 v[8:11], v[4:7], v[4:7], 0
	v_mfma_f32_16x16x32_bf16 v[12:15], v[4:7], v[4:7], 0
	v_mfma_f32_16x16x32_bf16 v[16:19], v[4:7], v[4:7], 0
	v_mfma_f32_32x32x16_bf16 v[20:35], v[4:7], v[4:7], 0
	v_mfma_f32_32x32x16_bf16 v[36:51], v[4:7], v[4:7], 0
	v_mfma_f32_32x32x16_bf16 v[52:67], v[4:7], v[4:7], 0
	v_mfma_f32_32x32x16_bf16 v[68:83], v[4:7], v[4:7], 0
	v_mfma_f32_32x32x16_bf16 v[84:99], v[4:7], v[4:7], 0
	v_mfma_f32_32x32x16_bf16 v[100:115], v[4:7], v[4:7], 0
	v_mfma_f32_32x32x16_bf16 v[116:131], v[4:7], v[4:7], 0
	s_addc_u32 s44, s23, 0
	s_mov_b32 s45, -2
	s_waitcnt lgkmcnt(0)
	s_waitcnt vmcnt(0)

;     __device__ __forceinline__ const char* pa(const Unit& u) const { return (const char*)(A + (size_t)u.pm * a_tile_stride + (size_t)((u.pn >> a_group_shift) * a_group_cols)); }
;     __device__ __forceinline__ const char* pb(const Unit& u) const { return (const char*)(Bt + (size_t)u.pn * b_tile_stride); }
;     __device__ __forceinline__ const char* pa(const Unit& u) const { return (const char*)(A + (size_t)u.pm * a_tile_stride + (size_t)u.pn * 512); }
; template <class PT, class Epi>
; __device__ __forceinline__ void gemm_phase_once(LAS unsigned char* lds, const PT& S, const Epi& E, bool epi_on) {
;     ...
;         const bool has_next = S.next(ui + 1, nxt);
;         const char* nA = has_next ? S.pa(nxt) : cA; const char* nB = has_next ? S.pb(nxt) : cB;
;         for (int t = 0; t < nt; t += 2) {
;             const bool last = (t == nt - 2);
;             const char* a1 = cA + (size_t)(t + 1) * kstep;
;             const char* a2 = last ? nA : cA + (size_t)(t + 2) * kstep; const char* b2 = last ? nB : cB + (size_t)(t + 2) * kstep;
;             const char* a3 = a2 + kstep; const char* b3 = b2 + kstep;
;     ...
; #pragma unroll
;         for (int a = 0; a < 2; ++a)
; #pragma unroll
;             for (int b = 0; b < 2; ++b)
; #pragma unroll
;                 for (int m = 0; m < 4; ++m)
; #pragma unroll
;                     for (int n = 0; n < 2; ++n) acc[a][b][m][n] = (f32x4){0.f, 0.f, 0.f, 0.f};
;         cur = nxt; cA = nA; cB = nB; ++ui;
.LBB0_3749:
	s_ashr_i32 s13, s12, 31
	v_cmp_lt_i64_e32 vcc, s[14:15], v[144:145]
	s_lshl_b64 s[14:15], s[12:13], 21
	s_add_u32 s14, s78, s14
	s_addc_u32 s15, s79, s15
	s_and_b64 s[16:17], vcc, exec
	s_cselect_b32 s13, s15, s19
	s_cselect_b32 s39, s14, s18
	s_ashr_i32 s9, s8, 31
	s_lshl_b64 s[16:17], s[8:9], 21
	s_add_u32 s16, s92, s16
	s_addc_u32 s17, s93, s17
	s_and_b64 s[22:23], vcc, exec
	s_cselect_b32 s9, s17, s21
	s_cselect_b32 s40, s16, s20
	s_add_u32 s18, s18, 0x100080
	s_addc_u32 s19, s19, 0
	s_add_u32 s41, s20, 0x100
	v_mov_b32_e32 v4, 0
	v_mov_b32_e32 v5, 0
	v_mov_b32_e32 v6, 0
	v_mov_b32_e32 v7, 0
	s_nop 1
	v_mfma_f32_16x16x32_bf16 v[8:11], v[4:7], v[4:7], 0
	v_mfma_f32_16x16x32_bf16 v[12:15], v[4:7], v[4:7], 0
	v_mfma_f32_16x16x32_bf16 v[16:19], v[4:7], v[4:7], 0
	v_mfma_f32_32x32x16_bf16 v[20:35], v[4:7], v[4:7], 0
	v_mfma_f32_32x32x16_bf16 v[36:51], v[4:7], v[4:7], 0
	v_mfma_f32_32x32x16_bf16 v[52:67], v[4:7], v[4:7], 0
	v_mfma_f32_32x32x16_bf16 v[68:83], v[4:7], v[4:7], 0
	v_mfma_f32_32x32x16_bf16 v[84:99], v[4:7], v[4:7], 0
	v_mfma_f32_32x32x16_bf16 v[100:115], v[4:7], v[4:7], 0
	v_mfma_f32_32x32x16_bf16 v[116:131], v[4:7], v[4:7], 0
	s_addc_u32 s42, s21, 0
	s_mov_b32 s43, -2
	s_waitcnt lgkmcnt(0)

;     __device__ __forceinline__ const char* pa(const Unit& u) const { return (const char*)(A + (size_t)u.pm * a_tile_stride + (size_t)((u.pn >> a_group_shift) * a_group_cols)); }
;     __device__ __forceinline__ const char* pb(const Unit& u) const { return (const char*)(Bt + (size_t)u.pn * b_tile_stride); }
;     __device__ __forceinline__ const char* pa(const Unit& u) const { return (const char*)(A + (size_t)u.pm * a_tile_stride + (size_t)u.pn * 512); }
; template <class PT, class Epi>
; __device__ __forceinline__ void gemm_phase_once(LAS unsigned char* lds, const PT& S, const Epi& E, bool epi_on) {
;     ...
;         const bool has_next = S.next(ui + 1, nxt);
;         const char* nA = has_next ? S.pa(nxt) : cA; const char* nB = has_next ? S.pb(nxt) : cB;
;         for (int t = 0; t < nt; t += 2) {
;             const bool last = (t == nt - 2);
;             const char* a1 = cA + (size_t)(t + 1) * kstep;
;             const char* a2 = last ? nA : cA + (size_t)(t + 2) * kstep; const char* b2 = last ? nB : cB + (size_t)(t + 2) * kstep;
;             const char* a3 = a2 + kstep; const char* b3 = b2 + kstep;
;     ...
; #pragma unroll
;         for (int a = 0; a < 2; ++a)
; #pragma unroll
;             for (int b = 0; b < 2; ++b)
; #pragma unroll
;                 for (int m = 0; m < 4; ++m)
; #pragma unroll
;                     for (int n = 0; n < 2; ++n) acc[a][b][m][n] = (f32x4){0.f, 0.f, 0.f, 0.f};
;         cur = nxt; cA = nA; cB = nB; ++ui;
.LBB0_3883:
	s_ashr_i32 s11, s10, 31
	v_cmp_lt_i64_e32 vcc, s[12:13], v[144:145]
	s_lshl_b64 s[12:13], s[10:11], 20
	s_add_u32 s12, s72, s12
	s_addc_u32 s13, s73, s13
	s_and_b64 s[14:15], vcc, exec
	s_cselect_b32 s11, s13, s19
	s_cselect_b32 s39, s12, s18
	s_ashr_i32 s9, s8, 31
	s_lshl_b64 s[14:15], s[8:9], 20
	s_add_u32 s14, s84, s14
	s_addc_u32 s15, s85, s15
	s_and_b64 s[22:23], vcc, exec
	s_cselect_b32 s9, s15, s21
	s_cselect_b32 s40, s14, s20
	s_add_u32 s18, s18, 0x80080
	s_addc_u32 s19, s19, 0
	s_add_u32 s41, s20, 0x100
	v_mov_b32_e32 v4, 0
	v_mov_b32_e32 v5, 0
	v_mov_b32_e32 v6, 0
	v_mov_b32_e32 v7, 0
	s_nop 1
	v_mfma_f32_16x16x32_bf16 v[8:11], v[4:7], v[4:7], 0
	v_mfma_f32_16x16x32_bf16 v[12:15], v[4:7], v[4:7], 0
	v_mfma_f32_16x16x32_bf16 v[16:19], v[4:7], v[4:7], 0
	v_mfma_f32_32x32x16_bf16 v[20:35], v[4:7], v[4:7], 0
	v_mfma_f32_32x32x16_bf16 v[36:51], v[4:7], v[4:7], 0
	v_mfma_f32_32x32x16_bf16 v[52:67], v[4:7], v[4:7], 0
	v_mfma_f32_32x32x16_bf16 v[68:83], v[4:7], v[4:7], 0
	v_mfma_f32_32x32x16_bf16 v[84:99], v[4:7], v[4:7], 0
	v_mfma_f32_32x32x16_bf16 v[100:115], v[4:7], v[4:7], 0
	v_mfma_f32_32x32x16_bf16 v[116:131], v[4:7], v[4:7], 0
	s_addc_u32 s42, s21, 0
	s_mov_b32 s43, -2
	s_waitcnt lgkmcnt(0)
	s_waitcnt vmcnt(0)

;     __device__ __forceinline__ const char* pa(const Unit& u) const { return (const char*)(A + (size_t)u.pm * a_tile_stride + (size_t)((u.pn >> a_group_shift) * a_group_cols)); }
;     __device__ __forceinline__ const char* pb(const Unit& u) const { return (const char*)(Bt + (size_t)u.pn * b_tile_stride); }
;     __device__ __forceinline__ const char* pa(const Unit& u) const { return (const char*)(A + (size_t)u.pm * a_tile_stride + (size_t)u.pn * 512); }
; template <class PT, class Epi>
; __device__ __forceinline__ void gemm_phase_once(LAS unsigned char* lds, const PT& S, const Epi& E, bool epi_on) {
;     ...
;         const bool has_next = S.next(ui + 1, nxt);
;         const char* nA = has_next ? S.pa(nxt) : cA; const char* nB = has_next ? S.pb(nxt) : cB;
;         for (int t = 0; t < nt; t += 2) {
;             const bool last = (t == nt - 2);
;             const char* a1 = cA + (size_t)(t + 1) * kstep;
;             const char* a2 = last ? nA : cA + (size_t)(t + 2) * kstep; const char* b2 = last ? nB : cB + (size_t)(t + 2) * kstep;
;             const char* a3 = a2 + kstep; const char* b3 = b2 + kstep;
;     ...
; #pragma unroll
;         for (int a = 0; a < 2; ++a)
; #pragma unroll
;             for (int b = 0; b < 2; ++b)
; #pragma unroll
;                 for (int m = 0; m < 4; ++m)
; #pragma unroll
;                     for (int n = 0; n < 2; ++n) acc[a][b][m][n] = (f32x4){0.f, 0.f, 0.f, 0.f};
;         cur = nxt; cA = nA; cB = nB; ++ui;
.LBB0_3906:
	s_ashr_i32 s13, s12, 31
	v_cmp_lt_i64_e64 s[24:25], s[14:15], 16
	s_lshl_b64 s[14:15], s[12:13], 20
	s_add_u32 s14, s81, s14
	s_addc_u32 s15, s96, s15
	s_and_b64 s[16:17], s[24:25], exec
	s_cselect_b32 s1, s15, s21
	s_cselect_b32 s13, s14, s20
	s_ashr_i32 s11, s10, 31
	s_lshl_b64 s[16:17], s[10:11], 20
	s_add_u32 s16, s82, s16
	s_addc_u32 s17, s83, s17
	s_and_b64 s[24:25], s[24:25], exec
	s_cselect_b32 s11, s17, s23
	s_cselect_b32 s19, s16, s22
	s_add_u32 s20, s20, 0x80080
	s_addc_u32 s21, s21, 0
	s_add_u32 s45, s22, 0x100
	v_mov_b32_e32 v4, 0
	v_mov_b32_e32 v5, 0
	v_mov_b32_e32 v6, 0
	v_mov_b32_e32 v7, 0
	s_nop 1
	v_mfma_f32_16x16x32_bf16 v[8:11], v[4:7], v[4:7], 0
	v_mfma_f32_16x16x32_bf16 v[12:15], v[4:7], v[4:7], 0
	v_mfma_f32_16x16x32_bf16 v[16:19], v[4:7], v[4:7], 0
	v_mfma_f32_32x32x16_bf16 v[20:35], v[4:7], v[4:7], 0
	v_mfma_f32_32x32x16_bf16 v[36:51], v[4:7], v[4:7], 0
	v_mfma_f32_32x32x16_bf16 v[52:67], v[4:7], v[4:7], 0
	v_mfma_f32_32x32x16_bf16 v[68:83], v[4:7], v[4:7], 0
	v_mfma_f32_32x32x16_bf16 v[84:99], v[4:7], v[4:7], 0
	v_mfma_f32_32x32x16_bf16 v[100:115], v[4:7], v[4:7], 0
	v_mfma_f32_32x32x16_bf16 v[116:131], v[4:7], v[4:7], 0
	s_addc_u32 s46, s23, 0
	s_mov_b32 s47, -2
	s_waitcnt lgkmcnt(0)

;     __device__ __forceinline__ const char* pa(const Unit& u) const { return (const char*)(A + (size_t)u.pm * a_tile_stride + (size_t)((u.pn >> a_group_shift) * a_group_cols)); }
;     __device__ __forceinline__ const char* pb(const Unit& u) const { return (const char*)(Bt + (size_t)u.pn * b_tile_stride); }
;     __device__ __forceinline__ const char* pa(const Unit& u) const { return (const char*)(A + (size_t)u.pm * a_tile_stride + (size_t)u.pn * 512); }
; template <class PT, class Epi>
; __device__ __forceinline__ void gemm_phase_once(LAS unsigned char* lds, const PT& S, const Epi& E, bool epi_on) {
;     ...
;         const bool has_next = S.next(ui + 1, nxt);
;         const char* nA = has_next ? S.pa(nxt) : cA; const char* nB = has_next ? S.pb(nxt) : cB;
;         for (int t = 0; t < nt; t += 2) {
;             const bool last = (t == nt - 2);
;             const char* a1 = cA + (size_t)(t + 1) * kstep;
;             const char* a2 = last ? nA : cA + (size_t)(t + 2) * kstep; const char* b2 = last ? nB : cB + (size_t)(t + 2) * kstep;
;             const char* a3 = a2 + kstep; const char* b3 = b2 + kstep;
;     ...
; #pragma unroll
;         for (int a = 0; a < 2; ++a)
; #pragma unroll
;             for (int b = 0; b < 2; ++b)
; #pragma unroll
;                 for (int m = 0; m < 4; ++m)
; #pragma unroll
;                     for (int n = 0; n < 2; ++n) acc[a][b][m][n] = (f32x4){0.f, 0.f, 0.f, 0.f};
;         cur = nxt; cA = nA; cB = nB; ++ui;
.LBB0_4222:
	s_ashr_i32 s13, s12, 31
	v_cmp_lt_i64_e32 vcc, s[14:15], v[144:145]
	s_lshl_b64 s[14:15], s[12:13], 18
	v_readlane_b32 s16, v254, 48
	v_readlane_b32 s17, v254, 49
	s_add_u32 s14, s16, s14
	s_addc_u32 s15, s17, s15
	s_and_b64 s[16:17], vcc, exec
	s_cselect_b32 s13, s15, s19
	s_cselect_b32 s39, s14, s18
	s_ashr_i32 s9, s8, 31
	s_lshl_b64 s[16:17], s[8:9], 18
	v_readlane_b32 s22, v254, 7
	v_readlane_b32 s23, v254, 8
	s_add_u32 s16, s22, s16
	s_addc_u32 s17, s23, s17
	s_and_b64 s[22:23], vcc, exec
	s_cselect_b32 s9, s17, s21
	s_cselect_b32 s40, s16, s20
	s_add_u32 s18, s18, 0x20080
	s_addc_u32 s19, s19, 0
	s_add_u32 s41, s20, 0x100
	v_mov_b32_e32 v4, 0
	v_mov_b32_e32 v5, 0
	v_mov_b32_e32 v6, 0
	v_mov_b32_e32 v7, 0
	s_nop 1
	v_mfma_f32_16x16x32_bf16 v[8:11], v[4:7], v[4:7], 0
	v_mfma_f32_16x16x32_bf16 v[12:15], v[4:7], v[4:7], 0
	v_mfma_f32_16x16x32_bf16 v[16:19], v[4:7], v[4:7], 0
	v_mfma_f32_32x32x16_bf16 v[20:35], v[4:7], v[4:7], 0
	v_mfma_f32_32x32x16_bf16 v[36:51], v[4:7], v[4:7], 0
	v_mfma_f32_32x32x16_bf16 v[52:67], v[4:7], v[4:7], 0
	v_mfma_f32_32x32x16_bf16 v[68:83], v[4:7], v[4:7], 0
	v_mfma_f32_32x32x16_bf16 v[84:99], v[4:7], v[4:7], 0
	v_mfma_f32_32x32x16_bf16 v[100:115], v[4:7], v[4:7], 0
	v_mfma_f32_32x32x16_bf16 v[116:131], v[4:7], v[4:7], 0
	s_addc_u32 s42, s21, 0
	s_mov_b32 s43, -2
	s_waitcnt lgkmcnt(0)

;     __device__ __forceinline__ const char* pa(const Unit& u) const { return (const char*)(A + (size_t)u.pm * a_tile_stride + (size_t)((u.pn >> a_group_shift) * a_group_cols)); }
;     __device__ __forceinline__ const char* pb(const Unit& u) const { return (const char*)(Bt + (size_t)u.pn * b_tile_stride); }
;     __device__ __forceinline__ const char* pa(const Unit& u) const { return (const char*)(A + (size_t)u.pm * a_tile_stride + (size_t)u.pn * 512); }
; template <class PT, class Epi>
; __device__ __forceinline__ void gemm_phase_once(LAS unsigned char* lds, const PT& S, const Epi& E, bool epi_on) {
;     ...
;         const bool has_next = S.next(ui + 1, nxt);
;         const char* nA = has_next ? S.pa(nxt) : cA; const char* nB = has_next ? S.pb(nxt) : cB;
;         for (int t = 0; t < nt; t += 2) {
;             const bool last = (t == nt - 2);
;             const char* a1 = cA + (size_t)(t + 1) * kstep;
;             const char* a2 = last ? nA : cA + (size_t)(t + 2) * kstep; const char* b2 = last ? nB : cB + (size_t)(t + 2) * kstep;
;             const char* a3 = a2 + kstep; const char* b3 = b2 + kstep;
;     ...
; #pragma unroll
;         for (int a = 0; a < 2; ++a)
; #pragma unroll
;             for (int b = 0; b < 2; ++b)
; #pragma unroll
;                 for (int m = 0; m < 4; ++m)
; #pragma unroll
;                     for (int n = 0; n < 2; ++n) acc[a][b][m][n] = (f32x4){0.f, 0.f, 0.f, 0.f};
;         cur = nxt; cA = nA; cB = nB; ++ui;
.LBB0_4349:
	s_ashr_i32 s27, s26, 31
	v_cmp_lt_i64_e32 vcc, s[28:29], v[154:155]
	s_lshl_b64 s[28:29], s[26:27], 20
	s_add_u32 s28, s72, s28
	s_addc_u32 s29, s73, s29
	s_and_b64 s[30:31], vcc, exec
	s_cselect_b32 s27, s29, s37
	s_cselect_b32 s35, s28, s36
	s_ashr_i32 s25, s24, 31
	s_lshl_b64 s[30:31], s[24:25], 20
	s_add_u32 s30, s76, s30
	s_addc_u32 s31, s77, s31
	s_and_b64 s[40:41], vcc, exec
	s_cselect_b32 s25, s31, s39
	s_cselect_b32 s62, s30, s38
	s_add_u32 s63, s38, 0x100
	v_mov_b32_e32 v4, 0
	v_mov_b32_e32 v5, 0
	v_mov_b32_e32 v6, 0
	v_mov_b32_e32 v7, 0
	s_nop 1
	v_mfma_f32_16x16x32_bf16 v[8:11], v[4:7], v[4:7], 0
	v_mfma_f32_16x16x32_bf16 v[12:15], v[4:7], v[4:7], 0
	v_mfma_f32_16x16x32_bf16 v[16:19], v[4:7], v[4:7], 0
	v_mfma_f32_32x32x16_bf16 v[20:35], v[4:7], v[4:7], 0
	v_mfma_f32_32x32x16_bf16 v[44:59], v[4:7], v[4:7], 0
	v_mfma_f32_32x32x16_bf16 v[60:75], v[4:7], v[4:7], 0
	v_mfma_f32_32x32x16_bf16 v[76:91], v[4:7], v[4:7], 0
	v_mfma_f32_32x32x16_bf16 v[92:107], v[4:7], v[4:7], 0
	v_mfma_f32_32x32x16_bf16 v[108:123], v[4:7], v[4:7], 0
	v_mfma_f32_32x32x16_bf16 v[124:139], v[4:7], v[4:7], 0
	s_addc_u32 s64, s39, 0
	s_mov_b32 s65, -2
	s_waitcnt lgkmcnt(0)
	s_waitcnt vmcnt(0)

;     __device__ __forceinline__ const char* pa(const Unit& u) const { return (const char*)(A + (size_t)u.pm * a_tile_stride + (size_t)((u.pn >> a_group_shift) * a_group_cols)); }
;     __device__ __forceinline__ const char* pb(const Unit& u) const { return (const char*)(Bt + (size_t)u.pn * b_tile_stride); }
;     __device__ __forceinline__ const char* pa(const Unit& u) const { return (const char*)(A + (size_t)u.pm * a_tile_stride + (size_t)u.pn * 512); }
; template <class PT, class Epi>
; __device__ __forceinline__ void gemm_phase_once(LAS unsigned char* lds, const PT& S, const Epi& E, bool epi_on) {
;     ...
;         const bool has_next = S.next(ui + 1, nxt);
;         const char* nA = has_next ? S.pa(nxt) : cA; const char* nB = has_next ? S.pb(nxt) : cB;
;         for (int t = 0; t < nt; t += 2) {
;             const bool last = (t == nt - 2);
;             const char* a1 = cA + (size_t)(t + 1) * kstep;
;             const char* a2 = last ? nA : cA + (size_t)(t + 2) * kstep; const char* b2 = last ? nB : cB + (size_t)(t + 2) * kstep;
;             const char* a3 = a2 + kstep; const char* b3 = b2 + kstep;
;     ...
; #pragma unroll
;         for (int a = 0; a < 2; ++a)
; #pragma unroll
;             for (int b = 0; b < 2; ++b)
; #pragma unroll
;                 for (int m = 0; m < 4; ++m)
; #pragma unroll
;                     for (int n = 0; n < 2; ++n) acc[a][b][m][n] = (f32x4){0.f, 0.f, 0.f, 0.f};
;         cur = nxt; cA = nA; cB = nB; ++ui;
.LBB0_4817:
	s_xor_b64 s[0:1], s[14:15], -1
	s_mov_b64 s[18:19], s[6:7]
	s_and_b64 s[6:7], s[14:15], exec
	s_mov_b64 s[16:17], s[8:9]
	s_cselect_b32 s8, s28, s28
	s_cselect_b32 s6, s29, s29
	s_ashr_i32 s9, s8, 31
	s_lshl_b64 s[8:9], s[8:9], 20
	s_add_u32 s8, s72, s8
	s_addc_u32 s9, s73, s9
	s_and_b64 s[36:37], s[14:15], exec
	s_cselect_b32 s13, s9, s17
	s_cselect_b32 s35, s8, s16
	s_ashr_i32 s7, s6, 31
	s_lshl_b64 s[6:7], s[6:7], 20
	v_readlane_b32 s36, v254, 5
	v_readlane_b32 s37, v254, 6
	s_add_u32 s6, s36, s6
	s_addc_u32 s7, s37, s7
	s_and_b64 s[14:15], s[14:15], exec
	s_cselect_b32 s36, s7, s19
	s_cselect_b32 s37, s6, s18
	s_add_u32 s14, s16, 0x80080
	s_addc_u32 s15, s17, 0
	s_add_u32 s38, s18, 0x100
	v_mov_b32_e32 v4, 0
	v_mov_b32_e32 v5, 0
	v_mov_b32_e32 v6, 0
	v_mov_b32_e32 v7, 0
	s_nop 1
	v_mfma_f32_16x16x32_bf16 v[8:11], v[4:7], v[4:7], 0
	v_mfma_f32_16x16x32_bf16 v[12:15], v[4:7], v[4:7], 0
	v_mfma_f32_16x16x32_bf16 v[16:19], v[4:7], v[4:7], 0
	v_mfma_f32_32x32x16_bf16 v[20:35], v[4:7], v[4:7], 0
	v_mfma_f32_32x32x16_bf16 v[36:51], v[4:7], v[4:7], 0
	v_mfma_f32_32x32x16_bf16 v[52:67], v[4:7], v[4:7], 0
	v_mfma_f32_32x32x16_bf16 v[68:83], v[4:7], v[4:7], 0
	v_mfma_f32_32x32x16_bf16 v[84:99], v[4:7], v[4:7], 0
	v_mfma_f32_32x32x16_bf16 v[100:115], v[4:7], v[4:7], 0
	v_mfma_f32_32x32x16_bf16 v[116:131], v[4:7], v[4:7], 0
	s_addc_u32 s39, s19, 0
	s_mov_b32 s40, -2
	s_waitcnt lgkmcnt(0)
	s_waitcnt vmcnt(0)

;     __device__ __forceinline__ const char* pa(const Unit& u) const { return (const char*)(A + (size_t)u.pm * a_tile_stride + (size_t)((u.pn >> a_group_shift) * a_group_cols)); }
;     __device__ __forceinline__ const char* pb(const Unit& u) const { return (const char*)(Bt + (size_t)u.pn * b_tile_stride); }
;     __device__ __forceinline__ const char* pa(const Unit& u) const { return (const char*)(A + (size_t)u.pm * a_tile_stride + (size_t)u.pn * 512); }
; template <class PT, class Epi>
; __device__ __forceinline__ void gemm_phase_once(LAS unsigned char* lds, const PT& S, const Epi& E, bool epi_on) {
;     ...
;         const bool has_next = S.next(ui + 1, nxt);
;         const char* nA = has_next ? S.pa(nxt) : cA; const char* nB = has_next ? S.pb(nxt) : cB;
;         for (int t = 0; t < nt; t += 2) {
;             const bool last = (t == nt - 2);
;             const char* a1 = cA + (size_t)(t + 1) * kstep;
;             const char* a2 = last ? nA : cA + (size_t)(t + 2) * kstep; const char* b2 = last ? nB : cB + (size_t)(t + 2) * kstep;
;             const char* a3 = a2 + kstep; const char* b3 = b2 + kstep;
;     ...
; #pragma unroll
;         for (int a = 0; a < 2; ++a)
; #pragma unroll
;             for (int b = 0; b < 2; ++b)
; #pragma unroll
;                 for (int m = 0; m < 4; ++m)
; #pragma unroll
;                     for (int n = 0; n < 2; ++n) acc[a][b][m][n] = (f32x4){0.f, 0.f, 0.f, 0.f};
;         cur = nxt; cA = nA; cB = nB; ++ui;
.LBB0_5017:
	s_ashr_i32 s13, s12, 31
	v_cmp_lt_i64_e32 vcc, s[14:15], v[152:153]
	s_lshl_b64 s[14:15], s[12:13], 20
	s_add_u32 s11, s2, s14
	s_addc_u32 s13, s3, s15
	s_lshl_b32 s14, s10, 8
	s_and_b32 s14, s14, 0xfffffe00
	s_ashr_i32 s15, s14, 31
	s_lshl_b64 s[14:15], s[14:15], 1
	s_add_u32 s14, s11, s14
	s_addc_u32 s15, s13, s15
	s_and_b64 s[16:17], vcc, exec
	s_cselect_b32 s13, s15, s21
	s_cselect_b32 s41, s14, s20
	s_ashr_i32 s11, s10, 31
	s_lshl_b64 s[16:17], s[10:11], 18
	v_readlane_b32 s24, v254, 52
	v_readlane_b32 s25, v254, 53
	s_add_u32 s16, s24, s16
	s_addc_u32 s17, s25, s17
	s_and_b64 s[24:25], vcc, exec
	s_cselect_b32 s11, s17, s23
	s_cselect_b32 s42, s16, s22
	s_add_u32 s20, s20, 0x80080
	s_addc_u32 s21, s21, 0
	s_add_u32 s43, s22, 0x100
	v_mov_b32_e32 v4, 0
	v_mov_b32_e32 v5, 0
	v_mov_b32_e32 v6, 0
	v_mov_b32_e32 v7, 0
	s_nop 1
	v_mfma_f32_16x16x32_bf16 v[8:11], v[4:7], v[4:7], 0
	v_mfma_f32_16x16x32_bf16 v[12:15], v[4:7], v[4:7], 0
	v_mfma_f32_16x16x32_bf16 v[16:19], v[4:7], v[4:7], 0
	v_mfma_f32_32x32x16_bf16 v[20:35], v[4:7], v[4:7], 0
	v_mfma_f32_32x32x16_bf16 v[36:51], v[4:7], v[4:7], 0
	v_mfma_f32_32x32x16_bf16 v[52:67], v[4:7], v[4:7], 0
	v_mfma_f32_32x32x16_bf16 v[76:91], v[4:7], v[4:7], 0
	v_mfma_f32_32x32x16_bf16 v[92:107], v[4:7], v[4:7], 0
	v_mfma_f32_32x32x16_bf16 v[108:123], v[4:7], v[4:7], 0
	v_mfma_f32_32x32x16_bf16 v[124:139], v[4:7], v[4:7], 0
	s_addc_u32 s44, s23, 0
	s_mov_b32 s45, -2
	s_waitcnt lgkmcnt(0)
	s_waitcnt vmcnt(0)

;     __device__ __forceinline__ const char* pa(const Unit& u) const { return (const char*)(A + (size_t)u.pm * a_tile_stride + (size_t)((u.pn >> a_group_shift) * a_group_cols)); }
;     __device__ __forceinline__ const char* pb(const Unit& u) const { return (const char*)(Bt + (size_t)u.pn * b_tile_stride); }
;     __device__ __forceinline__ const char* pa(const Unit& u) const { return (const char*)(A + (size_t)u.pm * a_tile_stride + (size_t)u.pn * 512); }
; template <class PT, class Epi>
; __device__ __forceinline__ void gemm_phase_once(LAS unsigned char* lds, const PT& S, const Epi& E, bool epi_on) {
;     ...
;         const bool has_next = S.next(ui + 1, nxt);
;         const char* nA = has_next ? S.pa(nxt) : cA; const char* nB = has_next ? S.pb(nxt) : cB;
;         for (int t = 0; t < nt; t += 2) {
;             const bool last = (t == nt - 2);
;             const char* a1 = cA + (size_t)(t + 1) * kstep;
;             const char* a2 = last ? nA : cA + (size_t)(t + 2) * kstep; const char* b2 = last ? nB : cB + (size_t)(t + 2) * kstep;
;             const char* a3 = a2 + kstep; const char* b3 = b2 + kstep;
;     ...
; #pragma unroll
;         for (int a = 0; a < 2; ++a)
; #pragma unroll
;             for (int b = 0; b < 2; ++b)
; #pragma unroll
;                 for (int m = 0; m < 4; ++m)
; #pragma unroll
;                     for (int n = 0; n < 2; ++n) acc[a][b][m][n] = (f32x4){0.f, 0.f, 0.f, 0.f};
.LBB0_5092:
	s_ashr_i32 s11, s10, 31
	v_cmp_lt_i64_e32 vcc, s[12:13], v[144:145]
	s_lshl_b64 s[12:13], s[10:11], 20
	s_add_u32 s12, s78, s12
	s_addc_u32 s13, s79, s13
	s_and_b64 s[14:15], vcc, exec
	s_cselect_b32 s11, s13, s19
	s_cselect_b32 s39, s12, s18
	s_ashr_i32 s9, s8, 31
	s_lshl_b64 s[14:15], s[8:9], 20
	s_add_u32 s14, s92, s14
	s_addc_u32 s15, s93, s15
	s_and_b64 s[22:23], vcc, exec
	s_cselect_b32 s9, s15, s21
	s_cselect_b32 s40, s14, s20
	s_add_u32 s18, s18, 0x80080
	s_addc_u32 s19, s19, 0
	s_add_u32 s41, s20, 0x100
	v_mov_b32_e32 v4, 0
	v_mov_b32_e32 v5, 0
	v_mov_b32_e32 v6, 0
	v_mov_b32_e32 v7, 0
	s_nop 1
	v_mfma_f32_16x16x32_bf16 v[8:11], v[4:7], v[4:7], 0
	v_mfma_f32_16x16x32_bf16 v[12:15], v[4:7], v[4:7], 0
	v_mfma_f32_16x16x32_bf16 v[16:19], v[4:7], v[4:7], 0
	v_mfma_f32_32x32x16_bf16 v[20:35], v[4:7], v[4:7], 0
	v_mfma_f32_32x32x16_bf16 v[36:51], v[4:7], v[4:7], 0
	v_mfma_f32_32x32x16_bf16 v[52:67], v[4:7], v[4:7], 0
	v_mfma_f32_32x32x16_bf16 v[68:83], v[4:7], v[4:7], 0
	v_mfma_f32_32x32x16_bf16 v[84:99], v[4:7], v[4:7], 0
	v_mfma_f32_32x32x16_bf16 v[100:115], v[4:7], v[4:7], 0
	v_mfma_f32_32x32x16_bf16 v[116:131], v[4:7], v[4:7], 0
	s_addc_u32 s42, s21, 0
	s_mov_b32 s43, -2
	s_waitcnt lgkmcnt(0)

;     __device__ __forceinline__ const char* pa(const Unit& u) const { return (const char*)(A + (size_t)u.pm * a_tile_stride + (size_t)((u.pn >> a_group_shift) * a_group_cols)); }
;     __device__ __forceinline__ const char* pb(const Unit& u) const { return (const char*)(Bt + (size_t)u.pn * b_tile_stride); }
;     __device__ __forceinline__ const char* pa(const Unit& u) const { return (const char*)(A + (size_t)u.pm * a_tile_stride + (size_t)u.pn * 512); }
; template <class PT, class Epi>
; __device__ __forceinline__ void gemm_phase_once(LAS unsigned char* lds, const PT& S, const Epi& E, bool epi_on) {
;     ...
;         const bool has_next = S.next(ui + 1, nxt);
;         const char* nA = has_next ? S.pa(nxt) : cA; const char* nB = has_next ? S.pb(nxt) : cB;
;         for (int t = 0; t < nt; t += 2) {
;             const bool last = (t == nt - 2);
;             const char* a1 = cA + (size_t)(t + 1) * kstep;
;             const char* a2 = last ? nA : cA + (size_t)(t + 2) * kstep; const char* b2 = last ? nB : cB + (size_t)(t + 2) * kstep;
;             const char* a3 = a2 + kstep; const char* b3 = b2 + kstep;
;     ...
; #pragma unroll
;         for (int a = 0; a < 2; ++a)
; #pragma unroll
;             for (int b = 0; b < 2; ++b)
; #pragma unroll
;                 for (int m = 0; m < 4; ++m)
; #pragma unroll
;                     for (int n = 0; n < 2; ++n) acc[a][b][m][n] = (f32x4){0.f, 0.f, 0.f, 0.f};
.LBB0_5226:
	s_ashr_i32 s11, s10, 31
	v_cmp_lt_i64_e32 vcc, s[12:13], v[144:145]
	s_lshl_b64 s[12:13], s[10:11], 20
	s_add_u32 s12, s72, s12
	s_addc_u32 s13, s73, s13
	s_and_b64 s[14:15], vcc, exec
	s_cselect_b32 s11, s13, s19
	s_cselect_b32 s40, s12, s18
	s_ashr_i32 s9, s8, 31
	s_lshl_b64 s[14:15], s[8:9], 20
	s_add_u32 s14, s84, s14
	s_addc_u32 s15, s85, s15
	s_and_b64 s[22:23], vcc, exec
	s_cselect_b32 s9, s15, s21
	s_cselect_b32 s41, s14, s20
	s_add_u32 s18, s18, 0x80080
	s_addc_u32 s19, s19, 0
	s_add_u32 s42, s20, 0x100
	v_mov_b32_e32 v4, 0
	v_mov_b32_e32 v5, 0
	v_mov_b32_e32 v6, 0
	v_mov_b32_e32 v7, 0
	s_nop 1
	v_mfma_f32_16x16x32_bf16 v[8:11], v[4:7], v[4:7], 0
	v_mfma_f32_16x16x32_bf16 v[12:15], v[4:7], v[4:7], 0
	v_mfma_f32_16x16x32_bf16 v[16:19], v[4:7], v[4:7], 0
	v_mfma_f32_32x32x16_bf16 v[20:35], v[4:7], v[4:7], 0
	v_mfma_f32_32x32x16_bf16 v[36:51], v[4:7], v[4:7], 0
	v_mfma_f32_32x32x16_bf16 v[52:67], v[4:7], v[4:7], 0
	v_mfma_f32_32x32x16_bf16 v[68:83], v[4:7], v[4:7], 0
	v_mfma_f32_32x32x16_bf16 v[84:99], v[4:7], v[4:7], 0
	v_mfma_f32_32x32x16_bf16 v[100:115], v[4:7], v[4:7], 0
	v_mfma_f32_32x32x16_bf16 v[116:131], v[4:7], v[4:7], 0
	s_addc_u32 s43, s21, 0
	s_mov_b32 s44, -2
	s_waitcnt lgkmcnt(0)
	s_waitcnt vmcnt(0)

;     __device__ __forceinline__ const char* pa(const Unit& u) const { return (const char*)(A + (size_t)u.pm * a_tile_stride + (size_t)((u.pn >> a_group_shift) * a_group_cols)); }
;     __device__ __forceinline__ const char* pb(const Unit& u) const { return (const char*)(Bt + (size_t)u.pn * b_tile_stride); }
;     __device__ __forceinline__ const char* pa(const Unit& u) const { return (const char*)(A + (size_t)u.pm * a_tile_stride + (size_t)u.pn * 512); }
; template <class PT, class Epi>
; __device__ __forceinline__ void gemm_phase_once(LAS unsigned char* lds, const PT& S, const Epi& E, bool epi_on) {
;     ...
;         const bool has_next = S.next(ui + 1, nxt);
;         const char* nA = has_next ? S.pa(nxt) : cA; const char* nB = has_next ? S.pb(nxt) : cB;
;         for (int t = 0; t < nt; t += 2) {
;             const bool last = (t == nt - 2);
;             const char* a1 = cA + (size_t)(t + 1) * kstep;
;             const char* a2 = last ? nA : cA + (size_t)(t + 2) * kstep; const char* b2 = last ? nB : cB + (size_t)(t + 2) * kstep;
;             const char* a3 = a2 + kstep; const char* b3 = b2 + kstep;
;     ...
; #pragma unroll
;         for (int a = 0; a < 2; ++a)
; #pragma unroll
;             for (int b = 0; b < 2; ++b)
; #pragma unroll
;                 for (int m = 0; m < 4; ++m)
; #pragma unroll
;                     for (int n = 0; n < 2; ++n) acc[a][b][m][n] = (f32x4){0.f, 0.f, 0.f, 0.f};
.LBB0_5455:
	s_ashr_i32 s19, s18, 31
	v_cmp_lt_i64_e32 vcc, s[20:21], v[142:143]
	s_lshl_b64 s[20:21], s[18:19], 18
	v_readlane_b32 s22, v254, 48
	v_readlane_b32 s23, v254, 49
	s_add_u32 s20, s22, s20
	s_addc_u32 s21, s23, s21
	s_and_b64 s[22:23], vcc, exec
	s_cselect_b32 s19, s21, s27
	s_cselect_b32 s51, s20, s26
	s_ashr_i32 s17, s16, 31
	s_lshl_b64 s[22:23], s[16:17], 18
	v_readlane_b32 s30, v254, 7
	v_readlane_b32 s31, v254, 8
	s_add_u32 s22, s30, s22
	s_addc_u32 s23, s31, s23
	s_and_b64 s[30:31], vcc, exec
	s_cselect_b32 s17, s23, s29
	s_cselect_b32 s52, s22, s28
	s_add_u32 s26, s26, 0x20080
	s_addc_u32 s27, s27, 0
	s_add_u32 s53, s28, 0x100
	v_mov_b32_e32 v2, 0
	v_mov_b32_e32 v3, 0
	v_mov_b32_e32 v4, 0
	v_mov_b32_e32 v5, 0
	s_nop 1
	v_mfma_f32_16x16x32_bf16 v[6:9], v[2:5], v[2:5], 0
	v_mfma_f32_16x16x32_bf16 v[10:13], v[2:5], v[2:5], 0
	v_mfma_f32_16x16x32_bf16 v[14:17], v[2:5], v[2:5], 0
	v_mfma_f32_32x32x16_bf16 v[18:33], v[2:5], v[2:5], 0
	v_mfma_f32_32x32x16_bf16 v[34:49], v[2:5], v[2:5], 0
	v_mfma_f32_32x32x16_bf16 v[50:65], v[2:5], v[2:5], 0
	v_mfma_f32_32x32x16_bf16 v[66:81], v[2:5], v[2:5], 0
	v_mfma_f32_32x32x16_bf16 v[82:97], v[2:5], v[2:5], 0
	v_mfma_f32_32x32x16_bf16 v[98:113], v[2:5], v[2:5], 0
	v_mfma_f32_32x32x16_bf16 v[114:129], v[2:5], v[2:5], 0
	s_addc_u32 s54, s29, 0
	s_mov_b32 s55, -2
	s_waitcnt lgkmcnt(0)

;     __device__ __forceinline__ const char* pa(const Unit& u) const { return (const char*)(A + (size_t)u.pm * a_tile_stride + (size_t)((u.pn >> a_group_shift) * a_group_cols)); }
;     __device__ __forceinline__ const char* pb(const Unit& u) const { return (const char*)(Bt + (size_t)u.pn * b_tile_stride); }
;     __device__ __forceinline__ const char* pa(const Unit& u) const { return (const char*)(A + (size_t)u.pm * a_tile_stride + (size_t)u.pn * 512); }
; template <class PT, class Epi>
; __device__ __forceinline__ void gemm_phase_once(LAS unsigned char* lds, const PT& S, const Epi& E, bool epi_on) {
;     ...
;         const bool has_next = S.next(ui + 1, nxt);
;         const char* nA = has_next ? S.pa(nxt) : cA; const char* nB = has_next ? S.pb(nxt) : cB;
;         for (int t = 0; t < nt; t += 2) {
;             const bool last = (t == nt - 2);
;             const char* a1 = cA + (size_t)(t + 1) * kstep;
;             const char* a2 = last ? nA : cA + (size_t)(t + 2) * kstep; const char* b2 = last ? nB : cB + (size_t)(t + 2) * kstep;
;             const char* a3 = a2 + kstep; const char* b3 = b2 + kstep;
;     ...
; #pragma unroll
;         for (int a = 0; a < 2; ++a)
; #pragma unroll
;             for (int b = 0; b < 2; ++b)
; #pragma unroll
;                 for (int m = 0; m < 4; ++m)
; #pragma unroll
;                     for (int n = 0; n < 2; ++n) acc[a][b][m][n] = (f32x4){0.f, 0.f, 0.f, 0.f};
.LBB0_5582:
	s_ashr_i32 s27, s26, 31
	v_cmp_lt_i64_e32 vcc, s[28:29], v[152:153]
	s_lshl_b64 s[28:29], s[26:27], 20
	s_add_u32 s28, s72, s28
	s_addc_u32 s29, s73, s29
	s_and_b64 s[30:31], vcc, exec
	s_cselect_b32 s27, s29, s37
	s_cselect_b32 s35, s28, s36
	s_ashr_i32 s25, s24, 31
	s_lshl_b64 s[30:31], s[24:25], 20
	s_add_u32 s30, s76, s30
	s_addc_u32 s31, s77, s31
	s_and_b64 s[40:41], vcc, exec
	s_cselect_b32 s25, s31, s39
	s_cselect_b32 s62, s30, s38
	s_add_u32 s63, s38, 0x100
	v_mov_b32_e32 v2, 0
	v_mov_b32_e32 v3, 0
	v_mov_b32_e32 v4, 0
	v_mov_b32_e32 v5, 0
	s_nop 1
	v_mfma_f32_16x16x32_bf16 v[6:9], v[2:5], v[2:5], 0
	v_mfma_f32_16x16x32_bf16 v[10:13], v[2:5], v[2:5], 0
	v_mfma_f32_16x16x32_bf16 v[14:17], v[2:5], v[2:5], 0
	v_mfma_f32_32x32x16_bf16 v[18:33], v[2:5], v[2:5], 0
	v_mfma_f32_32x32x16_bf16 v[34:49], v[2:5], v[2:5], 0
	v_mfma_f32_16x16x32_bf16 v[50:53], v[2:5], v[2:5], 0
	v_mfma_f32_16x16x32_bf16 v[54:57], v[2:5], v[2:5], 0
	v_mfma_f32_16x16x32_bf16 v[62:65], v[2:5], v[2:5], 0
	v_mfma_f32_16x16x32_bf16 v[66:69], v[2:5], v[2:5], 0
	v_mfma_f32_32x32x16_bf16 v[74:89], v[2:5], v[2:5], 0
	v_mfma_f32_32x32x16_bf16 v[90:105], v[2:5], v[2:5], 0
	v_mfma_f32_32x32x16_bf16 v[106:121], v[2:5], v[2:5], 0
	v_mfma_f32_32x32x16_bf16 v[122:137], v[2:5], v[2:5], 0
	s_addc_u32 s64, s39, 0
	s_mov_b32 s65, -2
	s_waitcnt vmcnt(0)
	s_waitcnt lgkmcnt(0)

;     __device__ __forceinline__ const char* pa(const Unit& u) const { return (const char*)(A + (size_t)u.pm * a_tile_stride + (size_t)((u.pn >> a_group_shift) * a_group_cols)); }
;     __device__ __forceinline__ const char* pb(const Unit& u) const { return (const char*)(Bt + (size_t)u.pn * b_tile_stride); }
;     __device__ __forceinline__ const char* pa(const Unit& u) const { return (const char*)(A + (size_t)u.pm * a_tile_stride + (size_t)u.pn * 512); }
; template <class PT, class Epi>
; __device__ __forceinline__ void gemm_phase_once(LAS unsigned char* lds, const PT& S, const Epi& E, bool epi_on) {
;     ...
;         const bool has_next = S.next(ui + 1, nxt);
;         const char* nA = has_next ? S.pa(nxt) : cA; const char* nB = has_next ? S.pb(nxt) : cB;
;         for (int t = 0; t < nt; t += 2) {
;             const bool last = (t == nt - 2);
;             const char* a1 = cA + (size_t)(t + 1) * kstep;
;             const char* a2 = last ? nA : cA + (size_t)(t + 2) * kstep; const char* b2 = last ? nB : cB + (size_t)(t + 2) * kstep;
;             const char* a3 = a2 + kstep; const char* b3 = b2 + kstep;
;     ...
; #pragma unroll
;         for (int a = 0; a < 2; ++a)
; #pragma unroll
;             for (int b = 0; b < 2; ++b)
; #pragma unroll
;                 for (int m = 0; m < 4; ++m)
; #pragma unroll
;                     for (int n = 0; n < 2; ++n) acc[a][b][m][n] = (f32x4){0.f, 0.f, 0.f, 0.f};
.LBB0_5741:
	s_add_u32 s18, s18, 0x160080
	s_addc_u32 s19, s19, 0
	s_add_u32 s47, s20, 0x100
	v_mov_b32_e32 v0, 0
	v_mov_b32_e32 v1, 0
	v_mov_b32_e32 v2, 0
	v_mov_b32_e32 v3, 0
	s_nop 1
	v_mfma_f32_16x16x32_bf16 v[4:7], v[0:3], v[0:3], 0
	v_mfma_f32_16x16x32_bf16 v[8:11], v[0:3], v[0:3], 0
	v_mfma_f32_16x16x32_bf16 v[12:15], v[0:3], v[0:3], 0
	v_mfma_f32_32x32x16_bf16 v[16:31], v[0:3], v[0:3], 0
	v_mfma_f32_32x32x16_bf16 v[32:47], v[0:3], v[0:3], 0
	v_mfma_f32_32x32x16_bf16 v[48:63], v[0:3], v[0:3], 0
	v_mfma_f32_32x32x16_bf16 v[64:79], v[0:3], v[0:3], 0
	v_mfma_f32_32x32x16_bf16 v[80:95], v[0:3], v[0:3], 0
	v_mfma_f32_32x32x16_bf16 v[96:111], v[0:3], v[0:3], 0
	v_mfma_f32_32x32x16_bf16 v[112:127], v[0:3], v[0:3], 0
	s_addc_u32 s48, s21, 0
	s_mov_b32 s49, -2
	s_waitcnt lgkmcnt(0)
